# attention: softmax of tile kt interleaved with the PV MFMAs of tile kt-1 inside each wave (P double-buffered in registers), on top of the rewritten GLA scan
# speedup vs baseline: 1.0023x; 1.0023x over previous
.LBB0_39:
	v_mov_b32_e32 v0, v220
	v_and_b32_e32 v4, 15, v0
	v_ashrrev_i32_e32 v1, 4, v0
	v_and_b32_e32 v6, 7, v0
	v_lshlrev_b32_e32 v10, 3, v4
	v_ashrrev_i32_e32 v5, 3, v0
	v_lshl_or_b32 v180, v1, 11, v10
	v_lshlrev_b32_e32 v10, 3, v6
	v_bfe_u32 v3, v0, 5, 1
	v_lshl_or_b32 v164, v5, 6, v10
	v_readlane_b32 s0, v251, 21
	v_readlane_b32 s1, v251, 22
	v_lshlrev_b64 v[0:1], 1, v[164:165]
	v_lshlrev_b32_e32 v164, 5, v3
	v_lshl_add_u64 v[190:191], s[0:1], 0, v[0:1]
	v_readlane_b32 s0, v251, 17
	v_readlane_b32 s1, v251, 18
	s_nop 1
	v_lshl_add_u64 v[192:193], s[0:1], 0, v[164:165]
	v_readlane_b32 s0, v251, 19
	v_readlane_b32 s1, v251, 20
	s_nop 1
	v_lshl_add_u64 v[194:195], s[0:1], 0, v[164:165]
	s_mov_b64 s[0:1], 0x39c6000
	v_lshl_add_u64 v[196:197], v[0:1], 0, s[0:1]
	v_add_u32_e32 v182, 0x10000, v180
	v_mov_b32_e32 v181, v165
	v_mov_b32_e32 v183, v165
	v_mov_b64_e32 v[0:1], 0xfe04000
	v_lshl_add_u64 v[198:199], v[180:181], 1, v[0:1]
	v_lshl_add_u64 v[200:201], v[182:183], 1, v[0:1]
	v_lshlrev_b32_e32 v2, 3, v3
	v_lshlrev_b32_e32 v164, 1, v2
	s_lshl_b32 s0, s28, 7
	s_and_b32 s70, s0, 0x380000
	s_lshl_b32 s0, s28, 12
	s_and_b32 s1, s24, 7
	s_and_b32 s0, s0, 0x7000000
	s_lshl_b32 s1, s1, 9
	v_lshl_add_u64 v[210:211], v[196:197], 0, s[70:71]
	s_or_b32 s70, s1, s0
	s_lshl_b32 s0, s5, 8
	s_add_i32 s43, s0, s25
	s_lshl_b32 s1, s29, 9
	v_or_b32_e32 v208, s43, v189
	v_lshl_add_u64 v[212:213], s[70:71], 0, v[198:199]
	v_lshl_add_u64 v[214:215], s[70:71], 0, v[200:201]
	v_lshl_add_u64 v[216:217], s[70:71], 0, v[202:203]
	v_lshl_add_u64 v[218:219], s[70:71], 0, v[204:205]
	s_and_b32 s70, s1, 0x7000
	v_ashrrev_i32_e32 v209, 31, v208
	v_lshl_add_u64 v[206:207], v[208:209], 0, s[70:71]
	v_mov_b64_e32 v[0:1], s[14:15]
	s_and_b32 s42, s29, 7
	v_mad_u64_u32 v[0:1], s[38:39], v206, s10, v[0:1]
	v_mad_i32_i24 v1, v207, s10, v1
	s_mul_i32 s38, s42, 0x180
	s_mov_b32 s39, s71
	v_lshl_add_u64 v[0:1], v[0:1], 0, s[38:39]
	v_lshlrev_b64 v[20:21], 7, v[206:207]
	v_lshl_add_u64 v[4:5], v[0:1], 0, v[164:165]
	v_lshl_add_u64 v[34:35], v[192:193], 0, v[20:21]
	v_lshl_add_u64 v[20:21], v[194:195], 0, v[20:21]
	global_load_dwordx4 v[132:135], v[4:5], off
	global_load_dwordx4 v[128:131], v[4:5], off offset:32
	global_load_dwordx4 v[124:127], v[4:5], off offset:64
	global_load_dwordx4 v[116:119], v[4:5], off offset:96
	global_load_dwordx4 v[112:115], v[4:5], off offset:128
	global_load_dwordx4 v[104:107], v[4:5], off offset:160
	global_load_dwordx4 v[100:103], v[4:5], off offset:192
	global_load_dwordx4 v[96:99], v[4:5], off offset:224
	global_load_dwordx4 v[8:11], v[4:5], off offset:256
	global_load_dwordx4 v[0:3], v[4:5], off offset:288
	global_load_dwordx4 v[12:15], v[4:5], off offset:320
	s_nop 0
	global_load_dwordx4 v[4:7], v[4:5], off offset:352
	s_nop 0
	global_load_dwordx4 v[16:19], v[34:35], off offset:16
	global_load_dwordx4 v[22:25], v[34:35], off
	global_load_dwordx4 v[26:29], v[20:21], off offset:16
	global_load_dwordx4 v[30:33], v[20:21], off
	s_lshl_b32 s1, s70, 12
	s_add_u32 s1, s96, s1
	s_addc_u32 s5, s97, 0
	s_lshl_b32 s7, s42, 9
	s_add_u32 s38, s1, s7
	s_addc_u32 s39, s5, 0
	s_lshl_b32 s70, s70, 7
	s_or_b32 s44, s43, 31
	s_or_b32 s45, s0, 0xc0
	s_mov_b32 s46, 0
	v_mov_b32_e32 v209, 0
	v_mov_b32_e32 v247, 0xf149f2ca
	s_mov_b32 s13, 0
	s_waitcnt vmcnt(0)
	v_and_b32_e32 v37, 0xffff0000, v8
	v_lshlrev_b32_e32 v36, 16, v8
	s_waitcnt vmcnt(5)
	v_and_b32_e32 v39, 0xffff0000, v12
	v_lshlrev_b32_e32 v38, 16, v12
	v_lshlrev_b32_e32 v8, 16, v13
	s_waitcnt vmcnt(0)
	v_pk_mul_f32 v[40:41], v[30:31], v[36:37]
	v_pk_mul_f32 v[30:31], v[30:31], v[38:39]
	v_pk_fma_f32 v[40:41], v[22:23], v[38:39], v[40:41]
	v_pk_fma_f32 v[22:23], v[22:23], v[36:37], v[30:31] neg_lo:[0,0,1] neg_hi:[0,0,1]
	v_cvt_pk_bf16_f32 v108, v40, v41
	v_cvt_pk_bf16_f32 v120, v22, v23
	v_and_b32_e32 v23, 0xffff0000, v9
	v_lshlrev_b32_e32 v22, 16, v9
	v_and_b32_e32 v9, 0xffff0000, v13
	v_pk_mul_f32 v[12:13], v[32:33], v[22:23]
	s_nop 0
	v_pk_fma_f32 v[12:13], v[24:25], v[8:9], v[12:13]
	v_pk_mul_f32 v[8:9], v[32:33], v[8:9]
	v_cvt_pk_bf16_f32 v109, v12, v13
	v_pk_fma_f32 v[8:9], v[24:25], v[22:23], v[8:9] neg_lo:[0,0,1] neg_hi:[0,0,1]
	v_and_b32_e32 v13, 0xffff0000, v14
	v_cvt_pk_bf16_f32 v121, v8, v9
	v_and_b32_e32 v9, 0xffff0000, v10
	v_lshlrev_b32_e32 v8, 16, v10
	v_lshlrev_b32_e32 v12, 16, v14
	v_pk_mul_f32 v[22:23], v[26:27], v[8:9]
	v_lshlrev_b32_e32 v10, 16, v15
	v_pk_fma_f32 v[22:23], v[16:17], v[12:13], v[22:23]
	v_pk_mul_f32 v[12:13], v[26:27], v[12:13]
	v_cvt_pk_bf16_f32 v110, v22, v23
	v_pk_fma_f32 v[8:9], v[16:17], v[8:9], v[12:13] neg_lo:[0,0,1] neg_hi:[0,0,1]
	v_and_b32_e32 v25, 0xffff0000, v0
	v_cvt_pk_bf16_f32 v122, v8, v9
	v_and_b32_e32 v9, 0xffff0000, v11
	v_lshlrev_b32_e32 v8, 16, v11
	v_and_b32_e32 v11, 0xffff0000, v15
	v_pk_mul_f32 v[12:13], v[28:29], v[8:9]
	v_lshlrev_b32_e32 v24, 16, v0
	v_pk_fma_f32 v[12:13], v[18:19], v[10:11], v[12:13]
	v_pk_mul_f32 v[10:11], v[28:29], v[10:11]
	v_cvt_pk_bf16_f32 v111, v12, v13
	v_pk_fma_f32 v[8:9], v[18:19], v[8:9], v[10:11] neg_lo:[0,0,1] neg_hi:[0,0,1]
	v_and_b32_e32 v27, 0xffff0000, v4
	v_cvt_pk_bf16_f32 v123, v8, v9
	global_load_dwordx4 v[8:11], v[34:35], off offset:80
	global_load_dwordx4 v[16:19], v[34:35], off offset:64
	global_load_dwordx4 v[12:15], v[20:21], off offset:80
	s_nop 0
	global_load_dwordx4 v[20:23], v[20:21], off offset:64
	v_lshlrev_b32_e32 v26, 16, v4
	v_lshlrev_b32_e32 v0, 16, v5
	s_waitcnt vmcnt(0)
	v_pk_mul_f32 v[28:29], v[20:21], v[24:25]
	v_pk_mul_f32 v[20:21], v[20:21], v[26:27]
	v_pk_fma_f32 v[28:29], v[16:17], v[26:27], v[28:29]
	v_pk_fma_f32 v[16:17], v[16:17], v[24:25], v[20:21] neg_lo:[0,0,1] neg_hi:[0,0,1]
	v_cvt_pk_bf16_f32 v136, v28, v29
	v_cvt_pk_bf16_f32 v140, v16, v17
	v_and_b32_e32 v17, 0xffff0000, v1
	v_lshlrev_b32_e32 v16, 16, v1
	v_and_b32_e32 v1, 0xffff0000, v5
	v_pk_mul_f32 v[4:5], v[22:23], v[16:17]
	s_nop 0
	v_pk_fma_f32 v[4:5], v[18:19], v[0:1], v[4:5]
	v_pk_mul_f32 v[0:1], v[22:23], v[0:1]
	v_cvt_pk_bf16_f32 v137, v4, v5
	v_pk_fma_f32 v[0:1], v[18:19], v[16:17], v[0:1] neg_lo:[0,0,1] neg_hi:[0,0,1]
	v_and_b32_e32 v5, 0xffff0000, v6
	v_cvt_pk_bf16_f32 v141, v0, v1
	v_and_b32_e32 v1, 0xffff0000, v2
	v_lshlrev_b32_e32 v0, 16, v2
	v_lshlrev_b32_e32 v4, 16, v6
	v_pk_mul_f32 v[16:17], v[12:13], v[0:1]
	v_lshlrev_b32_e32 v2, 16, v7
	v_pk_fma_f32 v[16:17], v[8:9], v[4:5], v[16:17]
	v_pk_mul_f32 v[4:5], v[12:13], v[4:5]
	v_cvt_pk_bf16_f32 v138, v16, v17
	v_pk_fma_f32 v[0:1], v[8:9], v[0:1], v[4:5] neg_lo:[0,0,1] neg_hi:[0,0,1]
	v_lshl_add_u64 v[16:17], v[180:181], 1, s[38:39]
	v_cvt_pk_bf16_f32 v142, v0, v1
	v_and_b32_e32 v1, 0xffff0000, v3
	v_lshlrev_b32_e32 v0, 16, v3
	v_and_b32_e32 v3, 0xffff0000, v7
	v_pk_mul_f32 v[4:5], v[14:15], v[0:1]
	global_load_dwordx4 v[16:19], v[16:17], off offset:256
	v_pk_fma_f32 v[4:5], v[10:11], v[2:3], v[4:5]
	v_pk_mul_f32 v[2:3], v[14:15], v[2:3]
	v_cvt_pk_bf16_f32 v139, v4, v5
	v_pk_fma_f32 v[0:1], v[10:11], v[0:1], v[2:3] neg_lo:[0,0,1] neg_hi:[0,0,1]
	s_nop 0
	v_cvt_pk_bf16_f32 v143, v0, v1
	v_lshl_add_u64 v[0:1], v[180:181], 1, s[38:39]
	global_load_dwordx4 v[4:7], v[0:1], off
	v_lshl_add_u64 v[0:1], v[182:183], 1, s[38:39]
	global_load_dwordx4 v[8:11], v[0:1], off
	v_lshl_add_u64 v[0:1], v[190:191], 0, s[70:71]
	global_load_dwordx4 v[12:15], v[0:1], off
	v_lshl_add_u64 v[0:1], v[182:183], 1, s[38:39]
	global_load_dwordx4 v[0:3], v[0:1], off offset:256
	s_waitcnt vmcnt(0)
	ds_write_b128 v244, v[4:7]
	s_waitcnt vmcnt(2)
	ds_write_b128 v244, v[8:11] offset:12800
	s_waitcnt vmcnt(1)
	ds_write_b128 v245, v[12:15] offset:256
	v_mov_b32_e32 v14, v165
	v_mov_b32_e32 v15, v165
	s_waitcnt vmcnt(0)
	s_movk_i32 s0, 320
	s_movk_i32 s1, 1280
	v_lshrrev_b32_e32 v216, 4, v220
	v_mul_u32_u24_e32 v216, s0, v216
	v_and_b32_e32 v248, 15, v220
	v_lshl_add_u32 v216, v248, 4, v216
	v_and_b32_e32 v217, 3, v220
	v_lshlrev_b32_e32 v217, 3, v217
	v_bfe_u32 v248, v220, 2, 2
	v_mad_u32_u24 v217, v248, s0, v217
	v_bfe_u32 v248, v220, 4, 1
	v_lshl_add_u32 v217, v248, 5, v217
	v_bfe_u32 v248, v220, 5, 1
	v_mad_u32_u24 v217, v248, s1, v217
	ds_write_b128 v216, v[16:19] offset:51200
	ds_write_b128 v216, v[0:3] offset:61440
	v_mov_b32_e32 v0, v165
	v_mov_b32_e32 v1, v165
	v_mov_b32_e32 v2, v165
	v_mov_b32_e32 v3, v165
	v_mov_b32_e32 v4, v165
	v_mov_b32_e32 v5, v165
	v_mov_b32_e32 v6, v165
	v_mov_b32_e32 v7, v165
	v_mov_b32_e32 v8, v165
	v_mov_b32_e32 v9, v165
	v_mov_b32_e32 v10, v165
	v_mov_b32_e32 v11, v165
	v_mov_b32_e32 v12, v165
	v_mov_b32_e32 v13, v165
	v_mov_b64_e32 v[30:31], v[14:15]
	v_mov_b64_e32 v[46:47], v[14:15]
	v_mov_b64_e32 v[62:63], v[14:15]
	v_mov_b64_e32 v[28:29], v[12:13]
	v_mov_b64_e32 v[26:27], v[10:11]
	v_mov_b64_e32 v[24:25], v[8:9]
	v_mov_b64_e32 v[22:23], v[6:7]
	v_mov_b64_e32 v[20:21], v[4:5]
	v_mov_b64_e32 v[18:19], v[2:3]
	v_mov_b64_e32 v[16:17], v[0:1]
	v_mov_b64_e32 v[44:45], v[12:13]
	v_mov_b64_e32 v[42:43], v[10:11]
	v_mov_b64_e32 v[40:41], v[8:9]
	v_mov_b64_e32 v[38:39], v[6:7]
	v_mov_b64_e32 v[36:37], v[4:5]
	v_mov_b64_e32 v[34:35], v[2:3]
	v_mov_b64_e32 v[32:33], v[0:1]
	v_mov_b64_e32 v[60:61], v[12:13]
	v_mov_b64_e32 v[58:59], v[10:11]
	v_mov_b64_e32 v[56:57], v[8:9]
	v_mov_b64_e32 v[54:55], v[6:7]
	v_mov_b64_e32 v[52:53], v[4:5]
	v_mov_b64_e32 v[50:51], v[2:3]
	v_mov_b64_e32 v[48:49], v[0:1]
	s_waitcnt lgkmcnt(0)
	s_barrier
	v_lshl_add_u64 v[248:249], s[20:21], 0, v[212:213]
	global_load_dwordx4 v[152:155], v[248:249], off
	v_lshl_add_u64 v[170:171], s[20:21], 0, v[214:215]
	global_load_dwordx4 v[156:159], v[170:171], off
	v_lshl_add_u64 v[218:219], s[20:21], 0, v[210:211]
	global_load_dwordx4 v[160:163], v[218:219], off
	global_load_dwordx4 v[144:147], v[248:249], off offset:256
	global_load_dwordx4 v[148:151], v[170:171], off offset:256
	s_mov_b64 s[38:39], 0x2000
	v_lshl_add_u64 v[210:211], v[210:211], 0, s[38:39]
	v_lshl_add_u64 v[212:213], v[212:213], 0, s[72:73]
	v_lshl_add_u64 v[214:215], v[214:215], 0, s[72:73]
.Lp_loop:
.Lp_body0:
	s_cmp_le_i32 s46, s44
	s_cselect_b64 s[0:1], -1, 0
	s_cbranch_scc0 .Lp_noqk_b0
	s_and_b32 s5, s13, 1
	s_mul_i32 s7, s5, 0x6400
	v_add_u32_e32 v250, s7, v243
	ds_read_b128 v[166:169], v250 offset:0
	ds_read_b128 v[172:175], v250 offset:12800
	ds_read_b128 v[176:179], v250 offset:32
	ds_read_b128 v[222:225], v250 offset:12832
	ds_read_b128 v[180:183], v250 offset:64
	ds_read_b128 v[184:187], v250 offset:12864
	ds_read_b128 v[190:193], v250 offset:96
	ds_read_b128 v[194:197], v250 offset:12896
	s_waitcnt lgkmcnt(7)
	v_mfma_f32_32x32x16_bf16 v[64:79], v[166:169], v[132:135], 0
	ds_read_b128 v[166:169], v250 offset:128
	s_waitcnt lgkmcnt(7)
	v_mfma_f32_32x32x16_bf16 v[80:95], v[172:175], v[132:135], 0
	ds_read_b128 v[172:175], v250 offset:12928
	s_waitcnt lgkmcnt(7)
	v_mfma_f32_32x32x16_bf16 v[64:79], v[176:179], v[128:131], v[64:79]
	ds_read_b128 v[176:179], v250 offset:160
	s_waitcnt lgkmcnt(7)
	v_mfma_f32_32x32x16_bf16 v[80:95], v[222:225], v[128:131], v[80:95]
	ds_read_b128 v[222:225], v250 offset:12960
	s_waitcnt lgkmcnt(7)
	v_mfma_f32_32x32x16_bf16 v[64:79], v[180:183], v[124:127], v[64:79]
	ds_read_b128 v[180:183], v250 offset:192
	s_waitcnt lgkmcnt(7)
	v_mfma_f32_32x32x16_bf16 v[80:95], v[184:187], v[124:127], v[80:95]
	ds_read_b128 v[184:187], v250 offset:12992
	s_waitcnt lgkmcnt(7)
	v_mfma_f32_32x32x16_bf16 v[64:79], v[190:193], v[116:119], v[64:79]
	ds_read_b128 v[190:193], v250 offset:224
	s_waitcnt lgkmcnt(7)
	v_mfma_f32_32x32x16_bf16 v[80:95], v[194:197], v[116:119], v[80:95]
	ds_read_b128 v[194:197], v250 offset:13024
	s_waitcnt lgkmcnt(7)
	v_mfma_f32_32x32x16_bf16 v[64:79], v[166:169], v[112:115], v[64:79]
	ds_read_b128 v[166:169], v250 offset:256
	s_waitcnt lgkmcnt(7)
	v_mfma_f32_32x32x16_bf16 v[80:95], v[172:175], v[112:115], v[80:95]
	ds_read_b128 v[172:175], v250 offset:13056
	s_waitcnt lgkmcnt(7)
	v_mfma_f32_32x32x16_bf16 v[64:79], v[176:179], v[104:107], v[64:79]
	ds_read_b128 v[176:179], v250 offset:288
	s_waitcnt lgkmcnt(7)
	v_mfma_f32_32x32x16_bf16 v[80:95], v[222:225], v[104:107], v[80:95]
	ds_read_b128 v[222:225], v250 offset:13088
	s_waitcnt lgkmcnt(7)
	v_mfma_f32_32x32x16_bf16 v[64:79], v[180:183], v[100:103], v[64:79]
	ds_read_b128 v[180:183], v250 offset:320
	s_waitcnt lgkmcnt(7)
	v_mfma_f32_32x32x16_bf16 v[80:95], v[184:187], v[100:103], v[80:95]
	ds_read_b128 v[184:187], v250 offset:13120
	s_waitcnt lgkmcnt(7)
	v_mfma_f32_32x32x16_bf16 v[64:79], v[190:193], v[96:99], v[64:79]
	ds_read_b128 v[190:193], v250 offset:352
	s_waitcnt lgkmcnt(7)
	v_mfma_f32_32x32x16_bf16 v[80:95], v[194:197], v[96:99], v[80:95]
	ds_read_b128 v[194:197], v250 offset:13152
	s_waitcnt lgkmcnt(7)
	v_mfma_f32_32x32x16_bf16 v[64:79], v[166:169], v[120:123], v[64:79]
	s_waitcnt lgkmcnt(6)
	v_mfma_f32_32x32x16_bf16 v[80:95], v[172:175], v[120:123], v[80:95]
	s_waitcnt lgkmcnt(5)
	v_mfma_f32_32x32x16_bf16 v[64:79], v[176:179], v[140:143], v[64:79]
	s_waitcnt lgkmcnt(4)
	v_mfma_f32_32x32x16_bf16 v[80:95], v[222:225], v[140:143], v[80:95]
	s_waitcnt lgkmcnt(3)
	v_mfma_f32_32x32x16_bf16 v[64:79], v[180:183], v[108:111], v[64:79]
	s_waitcnt lgkmcnt(2)
	v_mfma_f32_32x32x16_bf16 v[80:95], v[184:187], v[108:111], v[80:95]
	s_waitcnt lgkmcnt(1)
	v_mfma_f32_32x32x16_bf16 v[64:79], v[190:193], v[136:139], v[64:79]
	s_waitcnt lgkmcnt(0)
	v_mfma_f32_32x32x16_bf16 v[80:95], v[194:197], v[136:139], v[80:95]

.Lp_nostage_b0:
	s_andn2_b64 vcc, exec, s[0:1]
	s_cbranch_vccnz .Lp_novis_b0
	s_cmp_eq_u32 s46, 0
	s_cbranch_scc0 .Lp_mixed_b0
	s_add_i32 s0, s46, 63
	s_cmp_gt_i32 s0, s43
	s_cbranch_scc0 .Lp_nomask_b0f
	v_sub_u32_e32 v227, v208, v188
	v_subrev_u32_e32 v227, s46, v227
	v_cmp_gt_i32_e32 vcc, 0, v227
	v_cmp_gt_i32_e64 s[0:1], 1, v227
	v_cmp_gt_i32_e64 s[38:39], 2, v227
	v_cndmask_b32_e32 v64, v64, v226, vcc
	v_cmp_gt_i32_e32 vcc, 3, v227
	v_cndmask_b32_e64 v65, v65, v226, s[0:1]
	v_cmp_gt_i32_e64 s[0:1], 8, v227
	v_cndmask_b32_e64 v66, v66, v226, s[38:39]
	v_cmp_gt_i32_e64 s[38:39], 9, v227
	v_cndmask_b32_e32 v67, v67, v226, vcc
	v_cmp_gt_i32_e32 vcc, 10, v227
	v_cndmask_b32_e64 v68, v68, v226, s[0:1]
	v_cmp_gt_i32_e64 s[0:1], 11, v227
	v_cndmask_b32_e64 v69, v69, v226, s[38:39]
	v_cmp_gt_i32_e64 s[38:39], 16, v227
	v_cndmask_b32_e32 v70, v70, v226, vcc
	v_cmp_gt_i32_e32 vcc, 17, v227
	v_cndmask_b32_e64 v71, v71, v226, s[0:1]
	v_cmp_gt_i32_e64 s[0:1], 18, v227
	v_cndmask_b32_e64 v72, v72, v226, s[38:39]
	v_cmp_gt_i32_e64 s[38:39], 19, v227
	v_cndmask_b32_e32 v73, v73, v226, vcc
	v_cmp_gt_i32_e32 vcc, 24, v227
	v_cndmask_b32_e64 v74, v74, v226, s[0:1]
	v_cmp_gt_i32_e64 s[0:1], 25, v227
	v_cndmask_b32_e64 v75, v75, v226, s[38:39]
	v_cmp_gt_i32_e64 s[38:39], 26, v227
	v_cndmask_b32_e32 v76, v76, v226, vcc
	v_cmp_gt_i32_e32 vcc, 27, v227
	v_cndmask_b32_e64 v77, v77, v226, s[0:1]
	v_cmp_gt_i32_e64 s[0:1], 32, v227
	v_cndmask_b32_e64 v78, v78, v226, s[38:39]
	v_cmp_gt_i32_e64 s[38:39], 33, v227
	v_cndmask_b32_e32 v79, v79, v226, vcc
	v_cmp_gt_i32_e32 vcc, 34, v227
	v_cndmask_b32_e64 v80, v80, v226, s[0:1]
	v_cmp_gt_i32_e64 s[0:1], 35, v227
	v_cndmask_b32_e64 v81, v81, v226, s[38:39]
	v_cmp_gt_i32_e64 s[38:39], 40, v227
	v_cndmask_b32_e32 v82, v82, v226, vcc
	v_cmp_gt_i32_e32 vcc, 41, v227
	v_cndmask_b32_e64 v83, v83, v226, s[0:1]
	v_cmp_gt_i32_e64 s[0:1], 42, v227
	v_cndmask_b32_e64 v84, v84, v226, s[38:39]
	v_cmp_gt_i32_e64 s[38:39], 43, v227
	v_cndmask_b32_e32 v85, v85, v226, vcc
	v_cmp_gt_i32_e32 vcc, 48, v227
	v_cndmask_b32_e64 v86, v86, v226, s[0:1]
	v_cmp_gt_i32_e64 s[0:1], 49, v227
	v_cndmask_b32_e64 v87, v87, v226, s[38:39]
	v_cmp_gt_i32_e64 s[38:39], 50, v227
	v_cndmask_b32_e32 v88, v88, v226, vcc
	v_cmp_gt_i32_e32 vcc, 51, v227
	v_cndmask_b32_e64 v89, v89, v226, s[0:1]
	v_cmp_gt_i32_e64 s[0:1], 56, v227
	v_cndmask_b32_e64 v90, v90, v226, s[38:39]
	v_cmp_gt_i32_e64 s[38:39], 57, v227
	v_cndmask_b32_e32 v91, v91, v226, vcc
	v_cmp_gt_i32_e32 vcc, 58, v227
	v_cndmask_b32_e64 v92, v92, v226, s[0:1]
	v_cmp_gt_i32_e64 s[0:1], 59, v227
	v_cndmask_b32_e64 v93, v93, v226, s[38:39]
	s_nop 1
	v_cndmask_b32_e32 v94, v94, v226, vcc
	v_cndmask_b32_e64 v95, v95, v226, s[0:1]
.Lp_nomask_b0f:
	v_max3_f32 v227, v64, v65, v66
	v_max3_f32 v248, v73, v74, v75
	v_max3_f32 v249, v80, v81, v82
	v_max3_f32 v170, v89, v90, v91
	v_max3_f32 v227, v227, v67, v68
	v_max3_f32 v248, v248, v76, v77
	v_max3_f32 v249, v249, v83, v84
	v_max3_f32 v170, v170, v92, v93
	v_max3_f32 v227, v227, v69, v70
	v_max3_f32 v248, v248, v78, v79
	v_max3_f32 v249, v249, v85, v86
	v_max3_f32 v170, v170, v94, v95
	v_max3_f32 v227, v227, v71, v72
	v_max3_f32 v249, v249, v87, v88
	v_max3_f32 v227, v227, v248, v226
	v_max3_f32 v227, v227, v249, v170
	v_mov_b32_e32 v248, v227
	s_nop 1
	v_permlane32_swap_b32_e32 v227, v248
	v_max_f32_e32 v227, v227, v248
	v_mul_f32_e32 v227, 0x3dd53b94, v227
	v_max_f32_e32 v221, v247, v227
	v_sub_f32_e32 v170, v247, v221
	v_exp_f32_e32 v170, v170
	v_cmp_gt_f32_e32 vcc, v221, v247
	s_mov_b64 s[38:39], vcc
	v_fma_f32 v64, v64, s6, -v221
	v_fma_f32 v80, v80, s6, -v221
	v_exp_f32_e32 v64, v64
	v_exp_f32_e32 v80, v80
	v_fma_f32 v65, v65, s6, -v221
	v_fma_f32 v81, v81, s6, -v221
	v_add_f32_e32 v248, v64, v80
	v_exp_f32_e32 v65, v65
	v_exp_f32_e32 v81, v81
	v_mov_b32_e32 v249, v248
	v_fma_f32 v66, v66, s6, -v221
	v_fma_f32 v82, v82, s6, -v221
	v_add_f32_e32 v248, v65, v81
	v_exp_f32_e32 v66, v66
	v_exp_f32_e32 v82, v82
	v_add_f32_e32 v249, v248, v249
	v_fma_f32 v67, v67, s6, -v221
	v_fma_f32 v83, v83, s6, -v221
	v_add_f32_e32 v248, v66, v82
	v_exp_f32_e32 v67, v67
	v_exp_f32_e32 v83, v83
	v_add_f32_e32 v249, v248, v249
	v_fma_f32 v68, v68, s6, -v221
	v_fma_f32 v84, v84, s6, -v221
	v_add_f32_e32 v248, v67, v83
	v_exp_f32_e32 v68, v68
	v_exp_f32_e32 v84, v84
	v_add_f32_e32 v249, v248, v249
	v_fma_f32 v69, v69, s6, -v221
	v_fma_f32 v85, v85, s6, -v221
	v_add_f32_e32 v248, v68, v84
	v_exp_f32_e32 v69, v69
	v_exp_f32_e32 v85, v85
	v_add_f32_e32 v249, v248, v249
	v_fma_f32 v70, v70, s6, -v221
	v_fma_f32 v86, v86, s6, -v221
	v_add_f32_e32 v248, v69, v85
	v_exp_f32_e32 v70, v70
	v_exp_f32_e32 v86, v86
	v_add_f32_e32 v249, v248, v249
	v_fma_f32 v71, v71, s6, -v221
	v_fma_f32 v87, v87, s6, -v221
	v_add_f32_e32 v248, v70, v86
	v_exp_f32_e32 v71, v71
	v_exp_f32_e32 v87, v87
	v_add_f32_e32 v249, v248, v249
	v_fma_f32 v72, v72, s6, -v221
	v_fma_f32 v88, v88, s6, -v221
	v_add_f32_e32 v248, v71, v87
	v_exp_f32_e32 v72, v72
	v_exp_f32_e32 v88, v88
	v_add_f32_e32 v249, v248, v249
	v_fma_f32 v73, v73, s6, -v221
	v_fma_f32 v89, v89, s6, -v221
	v_add_f32_e32 v248, v72, v88
	v_exp_f32_e32 v73, v73
	v_exp_f32_e32 v89, v89
	v_add_f32_e32 v249, v248, v249
	v_fma_f32 v74, v74, s6, -v221
	v_fma_f32 v90, v90, s6, -v221
	v_add_f32_e32 v248, v73, v89
	v_exp_f32_e32 v74, v74
	v_exp_f32_e32 v90, v90
	v_add_f32_e32 v249, v248, v249
	v_fma_f32 v75, v75, s6, -v221
	v_fma_f32 v91, v91, s6, -v221
	v_add_f32_e32 v248, v74, v90
	v_exp_f32_e32 v75, v75
	v_exp_f32_e32 v91, v91
	v_add_f32_e32 v249, v248, v249
	v_fma_f32 v76, v76, s6, -v221
	v_fma_f32 v92, v92, s6, -v221
	v_add_f32_e32 v248, v75, v91
	v_exp_f32_e32 v76, v76
	v_exp_f32_e32 v92, v92
	v_add_f32_e32 v249, v248, v249
	v_fma_f32 v77, v77, s6, -v221
	v_fma_f32 v93, v93, s6, -v221
	v_add_f32_e32 v248, v76, v92
	v_exp_f32_e32 v77, v77
	v_exp_f32_e32 v93, v93
	v_add_f32_e32 v249, v248, v249
	v_fma_f32 v78, v78, s6, -v221
	v_fma_f32 v94, v94, s6, -v221
	v_add_f32_e32 v248, v77, v93
	v_exp_f32_e32 v78, v78
	v_exp_f32_e32 v94, v94
	v_add_f32_e32 v249, v248, v249
	v_fma_f32 v79, v79, s6, -v221
	v_fma_f32 v95, v95, s6, -v221
	v_add_f32_e32 v248, v78, v94
	v_exp_f32_e32 v79, v79
	v_exp_f32_e32 v95, v95
	v_add_f32_e32 v249, v248, v249
	s_nop 0
	v_add_f32_e32 v248, v79, v95
	v_add_f32_e32 v249, v248, v249
	v_fmac_f32_e32 v249, v209, v170
	v_cvt_pk_bf16_f32 v180, v64, v65
	v_cvt_pk_bf16_f32 v181, v66, v67
	v_cvt_pk_bf16_f32 v182, v68, v69
	v_cvt_pk_bf16_f32 v183, v70, v71
	v_cvt_pk_bf16_f32 v184, v72, v73
	v_cvt_pk_bf16_f32 v185, v74, v75
	v_cvt_pk_bf16_f32 v186, v76, v77
	v_cvt_pk_bf16_f32 v187, v78, v79
	v_cvt_pk_bf16_f32 v190, v80, v81
	v_cvt_pk_bf16_f32 v191, v82, v83
	v_cvt_pk_bf16_f32 v192, v84, v85
	v_cvt_pk_bf16_f32 v193, v86, v87
	v_cvt_pk_bf16_f32 v194, v88, v89
	v_cvt_pk_bf16_f32 v195, v90, v91
	v_cvt_pk_bf16_f32 v196, v92, v93
	v_cvt_pk_bf16_f32 v197, v94, v95
	v_mov_b32_e32 v209, v249
	v_mov_b32_e32 v247, v221
	s_and_b64 vcc, exec, s[38:39]
	s_cbranch_vccz .Lp_nr_b0f
	v_pk_mul_f32 v[62:63], v[62:63], v[170:171] op_sel_hi:[1,0]
	v_pk_mul_f32 v[60:61], v[60:61], v[170:171] op_sel_hi:[1,0]
	v_pk_mul_f32 v[58:59], v[58:59], v[170:171] op_sel_hi:[1,0]
	v_pk_mul_f32 v[56:57], v[56:57], v[170:171] op_sel_hi:[1,0]
	v_pk_mul_f32 v[54:55], v[54:55], v[170:171] op_sel_hi:[1,0]
	v_pk_mul_f32 v[52:53], v[52:53], v[170:171] op_sel_hi:[1,0]
	v_pk_mul_f32 v[50:51], v[50:51], v[170:171] op_sel_hi:[1,0]
	v_pk_mul_f32 v[48:49], v[48:49], v[170:171] op_sel_hi:[1,0]
	v_pk_mul_f32 v[46:47], v[46:47], v[170:171] op_sel_hi:[1,0]
	v_pk_mul_f32 v[44:45], v[44:45], v[170:171] op_sel_hi:[1,0]
	v_pk_mul_f32 v[42:43], v[42:43], v[170:171] op_sel_hi:[1,0]
	v_pk_mul_f32 v[40:41], v[40:41], v[170:171] op_sel_hi:[1,0]
	v_pk_mul_f32 v[38:39], v[38:39], v[170:171] op_sel_hi:[1,0]
	v_pk_mul_f32 v[36:37], v[36:37], v[170:171] op_sel_hi:[1,0]
	v_pk_mul_f32 v[34:35], v[34:35], v[170:171] op_sel_hi:[1,0]
	v_pk_mul_f32 v[32:33], v[32:33], v[170:171] op_sel_hi:[1,0]
	v_pk_mul_f32 v[30:31], v[30:31], v[170:171] op_sel_hi:[1,0]
	v_pk_mul_f32 v[28:29], v[28:29], v[170:171] op_sel_hi:[1,0]
	v_pk_mul_f32 v[26:27], v[26:27], v[170:171] op_sel_hi:[1,0]
	v_pk_mul_f32 v[24:25], v[24:25], v[170:171] op_sel_hi:[1,0]
	v_pk_mul_f32 v[22:23], v[22:23], v[170:171] op_sel_hi:[1,0]
	v_pk_mul_f32 v[20:21], v[20:21], v[170:171] op_sel_hi:[1,0]
	v_pk_mul_f32 v[18:19], v[18:19], v[170:171] op_sel_hi:[1,0]
	v_pk_mul_f32 v[16:17], v[16:17], v[170:171] op_sel_hi:[1,0]
	v_pk_mul_f32 v[14:15], v[14:15], v[170:171] op_sel_hi:[1,0]
	v_pk_mul_f32 v[12:13], v[12:13], v[170:171] op_sel_hi:[1,0]
	v_pk_mul_f32 v[10:11], v[10:11], v[170:171] op_sel_hi:[1,0]
	v_pk_mul_f32 v[8:9], v[8:9], v[170:171] op_sel_hi:[1,0]
	v_pk_mul_f32 v[6:7], v[6:7], v[170:171] op_sel_hi:[1,0]
	v_pk_mul_f32 v[4:5], v[4:5], v[170:171] op_sel_hi:[1,0]
	v_pk_mul_f32 v[2:3], v[2:3], v[170:171] op_sel_hi:[1,0]
	v_pk_mul_f32 v[0:1], v[0:1], v[170:171] op_sel_hi:[1,0]

.Lp_mixed_b0:
	s_add_i32 s5, s13, -1
	s_mul_i32 s38, s5, 43
	s_lshr_b32 s38, s38, 7
	s_mul_i32 s38, s38, 3
	s_sub_i32 s5, s5, s38
	s_mul_i32 s5, s5, 20480
	s_add_i32 s5, s5, 51200
	v_add_u32_e32 v250, s5, v217
	ds_read_b64_tr_b16 v[166:167], v250 offset:0
	ds_read_b64_tr_b16 v[168:169], v250 offset:2560
	ds_read_b64_tr_b16 v[172:173], v250 offset:5120
	ds_read_b64_tr_b16 v[174:175], v250 offset:7680
	ds_read_b64_tr_b16 v[176:177], v250 offset:10240
	ds_read_b64_tr_b16 v[178:179], v250 offset:12800
	ds_read_b64_tr_b16 v[222:223], v250 offset:15360
	ds_read_b64_tr_b16 v[224:225], v250 offset:17920
	s_add_i32 s0, s46, 63
	s_cmp_gt_i32 s0, s43
	s_cbranch_scc0 .Lp_nomask_b0m
	v_sub_u32_e32 v227, v208, v188
	v_subrev_u32_e32 v227, s46, v227
	v_cmp_gt_i32_e32 vcc, 0, v227
	v_cmp_gt_i32_e64 s[0:1], 1, v227
	v_cmp_gt_i32_e64 s[38:39], 2, v227
	v_cndmask_b32_e32 v64, v64, v226, vcc
	v_cmp_gt_i32_e32 vcc, 3, v227
	v_cndmask_b32_e64 v65, v65, v226, s[0:1]
	v_cmp_gt_i32_e64 s[0:1], 8, v227
	v_cndmask_b32_e64 v66, v66, v226, s[38:39]
	v_cmp_gt_i32_e64 s[38:39], 9, v227
	v_cndmask_b32_e32 v67, v67, v226, vcc
	v_cmp_gt_i32_e32 vcc, 10, v227
	v_cndmask_b32_e64 v68, v68, v226, s[0:1]
	v_cmp_gt_i32_e64 s[0:1], 11, v227
	v_cndmask_b32_e64 v69, v69, v226, s[38:39]
	v_cmp_gt_i32_e64 s[38:39], 16, v227
	v_cndmask_b32_e32 v70, v70, v226, vcc
	v_cmp_gt_i32_e32 vcc, 17, v227
	v_cndmask_b32_e64 v71, v71, v226, s[0:1]
	v_cmp_gt_i32_e64 s[0:1], 18, v227
	v_cndmask_b32_e64 v72, v72, v226, s[38:39]
	v_cmp_gt_i32_e64 s[38:39], 19, v227
	v_cndmask_b32_e32 v73, v73, v226, vcc
	v_cmp_gt_i32_e32 vcc, 24, v227
	v_cndmask_b32_e64 v74, v74, v226, s[0:1]
	v_cmp_gt_i32_e64 s[0:1], 25, v227
	v_cndmask_b32_e64 v75, v75, v226, s[38:39]
	v_cmp_gt_i32_e64 s[38:39], 26, v227
	v_cndmask_b32_e32 v76, v76, v226, vcc
	v_cmp_gt_i32_e32 vcc, 27, v227
	v_cndmask_b32_e64 v77, v77, v226, s[0:1]
	v_cmp_gt_i32_e64 s[0:1], 32, v227
	v_cndmask_b32_e64 v78, v78, v226, s[38:39]
	v_cmp_gt_i32_e64 s[38:39], 33, v227
	v_cndmask_b32_e32 v79, v79, v226, vcc
	v_cmp_gt_i32_e32 vcc, 34, v227
	v_cndmask_b32_e64 v80, v80, v226, s[0:1]
	v_cmp_gt_i32_e64 s[0:1], 35, v227
	v_cndmask_b32_e64 v81, v81, v226, s[38:39]
	v_cmp_gt_i32_e64 s[38:39], 40, v227
	v_cndmask_b32_e32 v82, v82, v226, vcc
	v_cmp_gt_i32_e32 vcc, 41, v227
	v_cndmask_b32_e64 v83, v83, v226, s[0:1]
	v_cmp_gt_i32_e64 s[0:1], 42, v227
	v_cndmask_b32_e64 v84, v84, v226, s[38:39]
	v_cmp_gt_i32_e64 s[38:39], 43, v227
	v_cndmask_b32_e32 v85, v85, v226, vcc
	v_cmp_gt_i32_e32 vcc, 48, v227
	v_cndmask_b32_e64 v86, v86, v226, s[0:1]
	v_cmp_gt_i32_e64 s[0:1], 49, v227
	v_cndmask_b32_e64 v87, v87, v226, s[38:39]
	v_cmp_gt_i32_e64 s[38:39], 50, v227
	v_cndmask_b32_e32 v88, v88, v226, vcc
	v_cmp_gt_i32_e32 vcc, 51, v227
	v_cndmask_b32_e64 v89, v89, v226, s[0:1]
	v_cmp_gt_i32_e64 s[0:1], 56, v227
	v_cndmask_b32_e64 v90, v90, v226, s[38:39]
	v_cmp_gt_i32_e64 s[38:39], 57, v227
	v_cndmask_b32_e32 v91, v91, v226, vcc
	v_cmp_gt_i32_e32 vcc, 58, v227
	v_cndmask_b32_e64 v92, v92, v226, s[0:1]
	v_cmp_gt_i32_e64 s[0:1], 59, v227
	v_cndmask_b32_e64 v93, v93, v226, s[38:39]
	s_nop 1
	v_cndmask_b32_e32 v94, v94, v226, vcc
	v_cndmask_b32_e64 v95, v95, v226, s[0:1]
.Lp_nomask_b0m:
	v_max3_f32 v227, v64, v65, v66
	v_max3_f32 v248, v73, v74, v75
	v_max3_f32 v249, v80, v81, v82
	v_max3_f32 v170, v89, v90, v91
	v_max3_f32 v227, v227, v67, v68
	v_max3_f32 v248, v248, v76, v77
	v_max3_f32 v249, v249, v83, v84
	v_max3_f32 v170, v170, v92, v93
	v_max3_f32 v227, v227, v69, v70
	s_waitcnt lgkmcnt(6)
	v_mfma_f32_32x32x16_bf16 v[48:63], v[166:169], v[198:201], v[48:63]
	ds_read_b64_tr_b16 v[166:167], v250 offset:64
	ds_read_b64_tr_b16 v[168:169], v250 offset:2624
	v_max3_f32 v248, v248, v78, v79
	v_max3_f32 v249, v249, v85, v86
	v_max3_f32 v170, v170, v94, v95
	v_max3_f32 v227, v227, v71, v72
	v_max3_f32 v249, v249, v87, v88
	v_max3_f32 v227, v227, v248, v226
	v_max3_f32 v227, v227, v249, v170
	v_mov_b32_e32 v248, v227
	s_nop 1
	s_waitcnt lgkmcnt(6)
	v_mfma_f32_32x32x16_bf16 v[48:63], v[172:175], v[202:205], v[48:63]
	ds_read_b64_tr_b16 v[172:173], v250 offset:5184
	ds_read_b64_tr_b16 v[174:175], v250 offset:7744
	v_permlane32_swap_b32_e32 v227, v248
	v_max_f32_e32 v227, v227, v248
	v_mul_f32_e32 v227, 0x3dd53b94, v227
	v_max_f32_e32 v221, v247, v227
	v_sub_f32_e32 v170, v247, v221
	v_exp_f32_e32 v170, v170
	v_cmp_gt_f32_e32 vcc, v221, v247
	s_mov_b64 s[38:39], vcc
	v_fma_f32 v64, v64, s6, -v221
	s_waitcnt lgkmcnt(6)
	v_mfma_f32_32x32x16_bf16 v[48:63], v[176:179], v[228:231], v[48:63]
	ds_read_b64_tr_b16 v[176:177], v250 offset:10304
	ds_read_b64_tr_b16 v[178:179], v250 offset:12864
	v_fma_f32 v80, v80, s6, -v221
	v_exp_f32_e32 v64, v64
	v_exp_f32_e32 v80, v80
	v_fma_f32 v65, v65, s6, -v221
	v_fma_f32 v81, v81, s6, -v221
	v_add_f32_e32 v248, v64, v80
	v_exp_f32_e32 v65, v65
	v_exp_f32_e32 v81, v81
	v_mov_b32_e32 v249, v248
	s_waitcnt lgkmcnt(6)
	v_mfma_f32_32x32x16_bf16 v[48:63], v[222:225], v[232:235], v[48:63]
	ds_read_b64_tr_b16 v[222:223], v250 offset:15424
	ds_read_b64_tr_b16 v[224:225], v250 offset:17984
	v_fma_f32 v66, v66, s6, -v221
	v_fma_f32 v82, v82, s6, -v221
	v_add_f32_e32 v248, v65, v81
	v_exp_f32_e32 v66, v66
	v_exp_f32_e32 v82, v82
	v_add_f32_e32 v249, v248, v249
	v_fma_f32 v67, v67, s6, -v221
	v_fma_f32 v83, v83, s6, -v221
	v_add_f32_e32 v248, v66, v82
	s_waitcnt lgkmcnt(6)
	v_mfma_f32_32x32x16_bf16 v[32:47], v[166:169], v[198:201], v[32:47]
	ds_read_b64_tr_b16 v[166:167], v250 offset:128
	ds_read_b64_tr_b16 v[168:169], v250 offset:2688
	v_exp_f32_e32 v67, v67
	v_exp_f32_e32 v83, v83
	v_add_f32_e32 v249, v248, v249
	v_fma_f32 v68, v68, s6, -v221
	v_fma_f32 v84, v84, s6, -v221
	v_add_f32_e32 v248, v67, v83
	v_exp_f32_e32 v68, v68
	v_exp_f32_e32 v84, v84
	v_add_f32_e32 v249, v248, v249
	s_waitcnt lgkmcnt(6)
	v_mfma_f32_32x32x16_bf16 v[32:47], v[172:175], v[202:205], v[32:47]
	ds_read_b64_tr_b16 v[172:173], v250 offset:5248
	ds_read_b64_tr_b16 v[174:175], v250 offset:7808
	v_fma_f32 v69, v69, s6, -v221
	v_fma_f32 v85, v85, s6, -v221
	v_add_f32_e32 v248, v68, v84
	v_exp_f32_e32 v69, v69
	v_exp_f32_e32 v85, v85
	v_add_f32_e32 v249, v248, v249
	v_fma_f32 v70, v70, s6, -v221
	v_fma_f32 v86, v86, s6, -v221
	v_add_f32_e32 v248, v69, v85
	s_waitcnt lgkmcnt(6)
	v_mfma_f32_32x32x16_bf16 v[32:47], v[176:179], v[228:231], v[32:47]
	ds_read_b64_tr_b16 v[176:177], v250 offset:10368
	ds_read_b64_tr_b16 v[178:179], v250 offset:12928
	v_exp_f32_e32 v70, v70
	v_exp_f32_e32 v86, v86
	v_add_f32_e32 v249, v248, v249
	v_fma_f32 v71, v71, s6, -v221
	v_fma_f32 v87, v87, s6, -v221
	v_add_f32_e32 v248, v70, v86
	v_exp_f32_e32 v71, v71
	v_exp_f32_e32 v87, v87
	v_add_f32_e32 v249, v248, v249
	s_waitcnt lgkmcnt(6)
	v_mfma_f32_32x32x16_bf16 v[32:47], v[222:225], v[232:235], v[32:47]
	ds_read_b64_tr_b16 v[222:223], v250 offset:15488
	ds_read_b64_tr_b16 v[224:225], v250 offset:18048
	v_fma_f32 v72, v72, s6, -v221
	v_fma_f32 v88, v88, s6, -v221
	v_add_f32_e32 v248, v71, v87
	v_exp_f32_e32 v72, v72
	v_exp_f32_e32 v88, v88
	v_add_f32_e32 v249, v248, v249
	v_fma_f32 v73, v73, s6, -v221
	v_fma_f32 v89, v89, s6, -v221
	v_add_f32_e32 v248, v72, v88
	s_waitcnt lgkmcnt(6)
	v_mfma_f32_32x32x16_bf16 v[16:31], v[166:169], v[198:201], v[16:31]
	ds_read_b64_tr_b16 v[166:167], v250 offset:192
	ds_read_b64_tr_b16 v[168:169], v250 offset:2752
	v_exp_f32_e32 v73, v73
	v_exp_f32_e32 v89, v89
	v_add_f32_e32 v249, v248, v249
	v_fma_f32 v74, v74, s6, -v221
	v_fma_f32 v90, v90, s6, -v221
	v_add_f32_e32 v248, v73, v89
	v_exp_f32_e32 v74, v74
	v_exp_f32_e32 v90, v90
	v_add_f32_e32 v249, v248, v249
	s_waitcnt lgkmcnt(6)
	v_mfma_f32_32x32x16_bf16 v[16:31], v[172:175], v[202:205], v[16:31]
	ds_read_b64_tr_b16 v[172:173], v250 offset:5312
	ds_read_b64_tr_b16 v[174:175], v250 offset:7872
	v_fma_f32 v75, v75, s6, -v221
	v_fma_f32 v91, v91, s6, -v221
	v_add_f32_e32 v248, v74, v90
	v_exp_f32_e32 v75, v75
	v_exp_f32_e32 v91, v91
	v_add_f32_e32 v249, v248, v249
	v_fma_f32 v76, v76, s6, -v221
	v_fma_f32 v92, v92, s6, -v221
	v_add_f32_e32 v248, v75, v91
	s_waitcnt lgkmcnt(6)
	v_mfma_f32_32x32x16_bf16 v[16:31], v[176:179], v[228:231], v[16:31]
	ds_read_b64_tr_b16 v[176:177], v250 offset:10432
	ds_read_b64_tr_b16 v[178:179], v250 offset:12992
	v_exp_f32_e32 v76, v76
	v_exp_f32_e32 v92, v92
	v_add_f32_e32 v249, v248, v249
	v_fma_f32 v77, v77, s6, -v221
	v_fma_f32 v93, v93, s6, -v221
	v_add_f32_e32 v248, v76, v92
	v_exp_f32_e32 v77, v77
	v_exp_f32_e32 v93, v93
	v_add_f32_e32 v249, v248, v249
	s_waitcnt lgkmcnt(6)
	v_mfma_f32_32x32x16_bf16 v[16:31], v[222:225], v[232:235], v[16:31]
	ds_read_b64_tr_b16 v[222:223], v250 offset:15552
	ds_read_b64_tr_b16 v[224:225], v250 offset:18112
	v_fma_f32 v78, v78, s6, -v221
	v_fma_f32 v94, v94, s6, -v221
	v_add_f32_e32 v248, v77, v93
	v_exp_f32_e32 v78, v78
	v_exp_f32_e32 v94, v94
	v_add_f32_e32 v249, v248, v249
	v_fma_f32 v79, v79, s6, -v221
	v_fma_f32 v95, v95, s6, -v221
	v_add_f32_e32 v248, v78, v94
	s_waitcnt lgkmcnt(6)
	v_mfma_f32_32x32x16_bf16 v[0:15], v[166:169], v[198:201], v[0:15]
	v_exp_f32_e32 v79, v79
	v_exp_f32_e32 v95, v95
	v_add_f32_e32 v249, v248, v249
	s_nop 0
	v_add_f32_e32 v248, v79, v95
	v_add_f32_e32 v249, v248, v249
	v_fmac_f32_e32 v249, v209, v170
	v_cvt_pk_bf16_f32 v180, v64, v65
	v_cvt_pk_bf16_f32 v181, v66, v67
	s_waitcnt lgkmcnt(4)
	v_mfma_f32_32x32x16_bf16 v[0:15], v[172:175], v[202:205], v[0:15]
	v_cvt_pk_bf16_f32 v182, v68, v69
	v_cvt_pk_bf16_f32 v183, v70, v71
	v_cvt_pk_bf16_f32 v184, v72, v73
	v_cvt_pk_bf16_f32 v185, v74, v75
	v_cvt_pk_bf16_f32 v186, v76, v77
	v_cvt_pk_bf16_f32 v187, v78, v79
	v_cvt_pk_bf16_f32 v190, v80, v81
	v_cvt_pk_bf16_f32 v191, v82, v83
	v_cvt_pk_bf16_f32 v192, v84, v85
	s_waitcnt lgkmcnt(2)
	v_mfma_f32_32x32x16_bf16 v[0:15], v[176:179], v[228:231], v[0:15]
	v_cvt_pk_bf16_f32 v193, v86, v87
	v_cvt_pk_bf16_f32 v194, v88, v89
	v_cvt_pk_bf16_f32 v195, v90, v91
	v_cvt_pk_bf16_f32 v196, v92, v93
	v_cvt_pk_bf16_f32 v197, v94, v95
	v_mov_b32_e32 v209, v249
	v_mov_b32_e32 v247, v221
	s_waitcnt lgkmcnt(0)
	v_mfma_f32_32x32x16_bf16 v[0:15], v[222:225], v[232:235], v[0:15]
	s_and_b64 vcc, exec, s[38:39]
	s_cbranch_vccz .Lp_nr_b0m
	v_pk_mul_f32 v[62:63], v[62:63], v[170:171] op_sel_hi:[1,0]
	v_pk_mul_f32 v[60:61], v[60:61], v[170:171] op_sel_hi:[1,0]
	v_pk_mul_f32 v[58:59], v[58:59], v[170:171] op_sel_hi:[1,0]
	v_pk_mul_f32 v[56:57], v[56:57], v[170:171] op_sel_hi:[1,0]
	v_pk_mul_f32 v[54:55], v[54:55], v[170:171] op_sel_hi:[1,0]
	v_pk_mul_f32 v[52:53], v[52:53], v[170:171] op_sel_hi:[1,0]
	v_pk_mul_f32 v[50:51], v[50:51], v[170:171] op_sel_hi:[1,0]
	v_pk_mul_f32 v[48:49], v[48:49], v[170:171] op_sel_hi:[1,0]
	v_pk_mul_f32 v[46:47], v[46:47], v[170:171] op_sel_hi:[1,0]
	v_pk_mul_f32 v[44:45], v[44:45], v[170:171] op_sel_hi:[1,0]
	v_pk_mul_f32 v[42:43], v[42:43], v[170:171] op_sel_hi:[1,0]
	v_pk_mul_f32 v[40:41], v[40:41], v[170:171] op_sel_hi:[1,0]
	v_pk_mul_f32 v[38:39], v[38:39], v[170:171] op_sel_hi:[1,0]
	v_pk_mul_f32 v[36:37], v[36:37], v[170:171] op_sel_hi:[1,0]
	v_pk_mul_f32 v[34:35], v[34:35], v[170:171] op_sel_hi:[1,0]
	v_pk_mul_f32 v[32:33], v[32:33], v[170:171] op_sel_hi:[1,0]
	v_pk_mul_f32 v[30:31], v[30:31], v[170:171] op_sel_hi:[1,0]
	v_pk_mul_f32 v[28:29], v[28:29], v[170:171] op_sel_hi:[1,0]
	v_pk_mul_f32 v[26:27], v[26:27], v[170:171] op_sel_hi:[1,0]
	v_pk_mul_f32 v[24:25], v[24:25], v[170:171] op_sel_hi:[1,0]
	v_pk_mul_f32 v[22:23], v[22:23], v[170:171] op_sel_hi:[1,0]
	v_pk_mul_f32 v[20:21], v[20:21], v[170:171] op_sel_hi:[1,0]
	v_pk_mul_f32 v[18:19], v[18:19], v[170:171] op_sel_hi:[1,0]
	v_pk_mul_f32 v[16:17], v[16:17], v[170:171] op_sel_hi:[1,0]
	v_pk_mul_f32 v[14:15], v[14:15], v[170:171] op_sel_hi:[1,0]
	v_pk_mul_f32 v[12:13], v[12:13], v[170:171] op_sel_hi:[1,0]
	v_pk_mul_f32 v[10:11], v[10:11], v[170:171] op_sel_hi:[1,0]
	v_pk_mul_f32 v[8:9], v[8:9], v[170:171] op_sel_hi:[1,0]
	v_pk_mul_f32 v[6:7], v[6:7], v[170:171] op_sel_hi:[1,0]
	v_pk_mul_f32 v[4:5], v[4:5], v[170:171] op_sel_hi:[1,0]
	v_pk_mul_f32 v[2:3], v[2:3], v[170:171] op_sel_hi:[1,0]
	v_pk_mul_f32 v[0:1], v[0:1], v[170:171] op_sel_hi:[1,0]

.Lp_novis_b0:
	s_cmp_eq_u32 s46, 0
	s_cbranch_scc1 .Lp_end_b0
	s_sub_i32 s0, s46, 64
	s_cmp_le_i32 s0, s44
	s_cbranch_scc0 .Lp_end_b0
	s_add_i32 s5, s13, -1
	s_mul_i32 s38, s5, 43
	s_lshr_b32 s38, s38, 7
	s_mul_i32 s38, s38, 3
	s_sub_i32 s5, s5, s38
	s_mul_i32 s5, s5, 20480
	s_add_i32 s5, s5, 51200
	v_add_u32_e32 v250, s5, v217
	ds_read_b64_tr_b16 v[166:167], v250 offset:0
	ds_read_b64_tr_b16 v[168:169], v250 offset:2560
	ds_read_b64_tr_b16 v[172:173], v250 offset:5120
	ds_read_b64_tr_b16 v[174:175], v250 offset:7680
	ds_read_b64_tr_b16 v[176:177], v250 offset:10240
	ds_read_b64_tr_b16 v[178:179], v250 offset:12800
	ds_read_b64_tr_b16 v[222:223], v250 offset:15360
	ds_read_b64_tr_b16 v[224:225], v250 offset:17920
	s_nop 1
	s_waitcnt lgkmcnt(6)
	v_mfma_f32_32x32x16_bf16 v[48:63], v[166:169], v[198:201], v[48:63]
	ds_read_b64_tr_b16 v[166:167], v250 offset:64
	ds_read_b64_tr_b16 v[168:169], v250 offset:2624
	s_waitcnt lgkmcnt(6)
	v_mfma_f32_32x32x16_bf16 v[48:63], v[172:175], v[202:205], v[48:63]
	ds_read_b64_tr_b16 v[172:173], v250 offset:5184
	ds_read_b64_tr_b16 v[174:175], v250 offset:7744
	s_waitcnt lgkmcnt(6)
	v_mfma_f32_32x32x16_bf16 v[48:63], v[176:179], v[228:231], v[48:63]
	ds_read_b64_tr_b16 v[176:177], v250 offset:10304
	ds_read_b64_tr_b16 v[178:179], v250 offset:12864
	s_waitcnt lgkmcnt(6)
	v_mfma_f32_32x32x16_bf16 v[48:63], v[222:225], v[232:235], v[48:63]
	ds_read_b64_tr_b16 v[222:223], v250 offset:15424
	ds_read_b64_tr_b16 v[224:225], v250 offset:17984
	s_waitcnt lgkmcnt(6)
	v_mfma_f32_32x32x16_bf16 v[32:47], v[166:169], v[198:201], v[32:47]
	ds_read_b64_tr_b16 v[166:167], v250 offset:128
	ds_read_b64_tr_b16 v[168:169], v250 offset:2688
	s_waitcnt lgkmcnt(6)
	v_mfma_f32_32x32x16_bf16 v[32:47], v[172:175], v[202:205], v[32:47]
	ds_read_b64_tr_b16 v[172:173], v250 offset:5248
	ds_read_b64_tr_b16 v[174:175], v250 offset:7808
	s_waitcnt lgkmcnt(6)
	v_mfma_f32_32x32x16_bf16 v[32:47], v[176:179], v[228:231], v[32:47]
	ds_read_b64_tr_b16 v[176:177], v250 offset:10368
	ds_read_b64_tr_b16 v[178:179], v250 offset:12928
	s_waitcnt lgkmcnt(6)
	v_mfma_f32_32x32x16_bf16 v[32:47], v[222:225], v[232:235], v[32:47]
	ds_read_b64_tr_b16 v[222:223], v250 offset:15488
	ds_read_b64_tr_b16 v[224:225], v250 offset:18048
	s_waitcnt lgkmcnt(6)
	v_mfma_f32_32x32x16_bf16 v[16:31], v[166:169], v[198:201], v[16:31]
	ds_read_b64_tr_b16 v[166:167], v250 offset:192
	ds_read_b64_tr_b16 v[168:169], v250 offset:2752
	s_waitcnt lgkmcnt(6)
	v_mfma_f32_32x32x16_bf16 v[16:31], v[172:175], v[202:205], v[16:31]
	ds_read_b64_tr_b16 v[172:173], v250 offset:5312
	ds_read_b64_tr_b16 v[174:175], v250 offset:7872
	s_waitcnt lgkmcnt(6)
	v_mfma_f32_32x32x16_bf16 v[16:31], v[176:179], v[228:231], v[16:31]
	ds_read_b64_tr_b16 v[176:177], v250 offset:10432
	ds_read_b64_tr_b16 v[178:179], v250 offset:12992
	s_waitcnt lgkmcnt(6)
	v_mfma_f32_32x32x16_bf16 v[16:31], v[222:225], v[232:235], v[16:31]
	ds_read_b64_tr_b16 v[222:223], v250 offset:15552
	ds_read_b64_tr_b16 v[224:225], v250 offset:18112
	s_waitcnt lgkmcnt(6)
	v_mfma_f32_32x32x16_bf16 v[0:15], v[166:169], v[198:201], v[0:15]
	s_waitcnt lgkmcnt(4)
	v_mfma_f32_32x32x16_bf16 v[0:15], v[172:175], v[202:205], v[0:15]
	s_waitcnt lgkmcnt(2)
	v_mfma_f32_32x32x16_bf16 v[0:15], v[176:179], v[228:231], v[0:15]
	s_waitcnt lgkmcnt(0)
	v_mfma_f32_32x32x16_bf16 v[0:15], v[222:225], v[232:235], v[0:15]

.Lp_body1:
	s_cmp_le_i32 s46, s44
	s_cselect_b64 s[0:1], -1, 0
	s_cbranch_scc0 .Lp_noqk_b1
	s_and_b32 s5, s13, 1
	s_mul_i32 s7, s5, 0x6400
	v_add_u32_e32 v250, s7, v243
	ds_read_b128 v[166:169], v250 offset:0
	ds_read_b128 v[172:175], v250 offset:12800
	ds_read_b128 v[176:179], v250 offset:32
	ds_read_b128 v[222:225], v250 offset:12832
	ds_read_b128 v[198:201], v250 offset:64
	ds_read_b128 v[202:205], v250 offset:12864
	ds_read_b128 v[228:231], v250 offset:96
	ds_read_b128 v[232:235], v250 offset:12896
	s_waitcnt lgkmcnt(7)
	v_mfma_f32_32x32x16_bf16 v[64:79], v[166:169], v[132:135], 0
	ds_read_b128 v[166:169], v250 offset:128
	s_waitcnt lgkmcnt(7)
	v_mfma_f32_32x32x16_bf16 v[80:95], v[172:175], v[132:135], 0
	ds_read_b128 v[172:175], v250 offset:12928
	s_waitcnt lgkmcnt(7)
	v_mfma_f32_32x32x16_bf16 v[64:79], v[176:179], v[128:131], v[64:79]
	ds_read_b128 v[176:179], v250 offset:160
	s_waitcnt lgkmcnt(7)
	v_mfma_f32_32x32x16_bf16 v[80:95], v[222:225], v[128:131], v[80:95]
	ds_read_b128 v[222:225], v250 offset:12960
	s_waitcnt lgkmcnt(7)
	v_mfma_f32_32x32x16_bf16 v[64:79], v[198:201], v[124:127], v[64:79]
	ds_read_b128 v[198:201], v250 offset:192
	s_waitcnt lgkmcnt(7)
	v_mfma_f32_32x32x16_bf16 v[80:95], v[202:205], v[124:127], v[80:95]
	ds_read_b128 v[202:205], v250 offset:12992
	s_waitcnt lgkmcnt(7)
	v_mfma_f32_32x32x16_bf16 v[64:79], v[228:231], v[116:119], v[64:79]
	ds_read_b128 v[228:231], v250 offset:224
	s_waitcnt lgkmcnt(7)
	v_mfma_f32_32x32x16_bf16 v[80:95], v[232:235], v[116:119], v[80:95]
	ds_read_b128 v[232:235], v250 offset:13024
	s_waitcnt lgkmcnt(7)
	v_mfma_f32_32x32x16_bf16 v[64:79], v[166:169], v[112:115], v[64:79]
	ds_read_b128 v[166:169], v250 offset:256
	s_waitcnt lgkmcnt(7)
	v_mfma_f32_32x32x16_bf16 v[80:95], v[172:175], v[112:115], v[80:95]
	ds_read_b128 v[172:175], v250 offset:13056
	s_waitcnt lgkmcnt(7)
	v_mfma_f32_32x32x16_bf16 v[64:79], v[176:179], v[104:107], v[64:79]
	ds_read_b128 v[176:179], v250 offset:288
	s_waitcnt lgkmcnt(7)
	v_mfma_f32_32x32x16_bf16 v[80:95], v[222:225], v[104:107], v[80:95]
	ds_read_b128 v[222:225], v250 offset:13088
	s_waitcnt lgkmcnt(7)
	v_mfma_f32_32x32x16_bf16 v[64:79], v[198:201], v[100:103], v[64:79]
	ds_read_b128 v[198:201], v250 offset:320
	s_waitcnt lgkmcnt(7)
	v_mfma_f32_32x32x16_bf16 v[80:95], v[202:205], v[100:103], v[80:95]
	ds_read_b128 v[202:205], v250 offset:13120
	s_waitcnt lgkmcnt(7)
	v_mfma_f32_32x32x16_bf16 v[64:79], v[228:231], v[96:99], v[64:79]
	ds_read_b128 v[228:231], v250 offset:352
	s_waitcnt lgkmcnt(7)
	v_mfma_f32_32x32x16_bf16 v[80:95], v[232:235], v[96:99], v[80:95]
	ds_read_b128 v[232:235], v250 offset:13152
	s_waitcnt lgkmcnt(7)
	v_mfma_f32_32x32x16_bf16 v[64:79], v[166:169], v[120:123], v[64:79]
	s_waitcnt lgkmcnt(6)
	v_mfma_f32_32x32x16_bf16 v[80:95], v[172:175], v[120:123], v[80:95]
	s_waitcnt lgkmcnt(5)
	v_mfma_f32_32x32x16_bf16 v[64:79], v[176:179], v[140:143], v[64:79]
	s_waitcnt lgkmcnt(4)
	v_mfma_f32_32x32x16_bf16 v[80:95], v[222:225], v[140:143], v[80:95]
	s_waitcnt lgkmcnt(3)
	v_mfma_f32_32x32x16_bf16 v[64:79], v[198:201], v[108:111], v[64:79]
	s_waitcnt lgkmcnt(2)
	v_mfma_f32_32x32x16_bf16 v[80:95], v[202:205], v[108:111], v[80:95]
	s_waitcnt lgkmcnt(1)
	v_mfma_f32_32x32x16_bf16 v[64:79], v[228:231], v[136:139], v[64:79]
	s_waitcnt lgkmcnt(0)
	v_mfma_f32_32x32x16_bf16 v[80:95], v[232:235], v[136:139], v[80:95]

.Lp_nomask_b1f:
	v_max3_f32 v227, v64, v65, v66
	v_max3_f32 v248, v73, v74, v75
	v_max3_f32 v249, v80, v81, v82
	v_max3_f32 v170, v89, v90, v91
	v_max3_f32 v227, v227, v67, v68
	v_max3_f32 v248, v248, v76, v77
	v_max3_f32 v249, v249, v83, v84
	v_max3_f32 v170, v170, v92, v93
	v_max3_f32 v227, v227, v69, v70
	v_max3_f32 v248, v248, v78, v79
	v_max3_f32 v249, v249, v85, v86
	v_max3_f32 v170, v170, v94, v95
	v_max3_f32 v227, v227, v71, v72
	v_max3_f32 v249, v249, v87, v88
	v_max3_f32 v227, v227, v248, v226
	v_max3_f32 v227, v227, v249, v170
	v_mov_b32_e32 v248, v227
	s_nop 1
	v_permlane32_swap_b32_e32 v227, v248
	v_max_f32_e32 v227, v227, v248
	v_mul_f32_e32 v227, 0x3dd53b94, v227
	v_max_f32_e32 v221, v247, v227
	v_sub_f32_e32 v170, v247, v221
	v_exp_f32_e32 v170, v170
	v_cmp_gt_f32_e32 vcc, v221, v247
	s_mov_b64 s[38:39], vcc
	v_fma_f32 v64, v64, s6, -v221
	v_fma_f32 v80, v80, s6, -v221
	v_exp_f32_e32 v64, v64
	v_exp_f32_e32 v80, v80
	v_fma_f32 v65, v65, s6, -v221
	v_fma_f32 v81, v81, s6, -v221
	v_add_f32_e32 v248, v64, v80
	v_exp_f32_e32 v65, v65
	v_exp_f32_e32 v81, v81
	v_mov_b32_e32 v249, v248
	v_fma_f32 v66, v66, s6, -v221
	v_fma_f32 v82, v82, s6, -v221
	v_add_f32_e32 v248, v65, v81
	v_exp_f32_e32 v66, v66
	v_exp_f32_e32 v82, v82
	v_add_f32_e32 v249, v248, v249
	v_fma_f32 v67, v67, s6, -v221
	v_fma_f32 v83, v83, s6, -v221
	v_add_f32_e32 v248, v66, v82
	v_exp_f32_e32 v67, v67
	v_exp_f32_e32 v83, v83
	v_add_f32_e32 v249, v248, v249
	v_fma_f32 v68, v68, s6, -v221
	v_fma_f32 v84, v84, s6, -v221
	v_add_f32_e32 v248, v67, v83
	v_exp_f32_e32 v68, v68
	v_exp_f32_e32 v84, v84
	v_add_f32_e32 v249, v248, v249
	v_fma_f32 v69, v69, s6, -v221
	v_fma_f32 v85, v85, s6, -v221
	v_add_f32_e32 v248, v68, v84
	v_exp_f32_e32 v69, v69
	v_exp_f32_e32 v85, v85
	v_add_f32_e32 v249, v248, v249
	v_fma_f32 v70, v70, s6, -v221
	v_fma_f32 v86, v86, s6, -v221
	v_add_f32_e32 v248, v69, v85
	v_exp_f32_e32 v70, v70
	v_exp_f32_e32 v86, v86
	v_add_f32_e32 v249, v248, v249
	v_fma_f32 v71, v71, s6, -v221
	v_fma_f32 v87, v87, s6, -v221
	v_add_f32_e32 v248, v70, v86
	v_exp_f32_e32 v71, v71
	v_exp_f32_e32 v87, v87
	v_add_f32_e32 v249, v248, v249
	v_fma_f32 v72, v72, s6, -v221
	v_fma_f32 v88, v88, s6, -v221
	v_add_f32_e32 v248, v71, v87
	v_exp_f32_e32 v72, v72
	v_exp_f32_e32 v88, v88
	v_add_f32_e32 v249, v248, v249
	v_fma_f32 v73, v73, s6, -v221
	v_fma_f32 v89, v89, s6, -v221
	v_add_f32_e32 v248, v72, v88
	v_exp_f32_e32 v73, v73
	v_exp_f32_e32 v89, v89
	v_add_f32_e32 v249, v248, v249
	v_fma_f32 v74, v74, s6, -v221
	v_fma_f32 v90, v90, s6, -v221
	v_add_f32_e32 v248, v73, v89
	v_exp_f32_e32 v74, v74
	v_exp_f32_e32 v90, v90
	v_add_f32_e32 v249, v248, v249
	v_fma_f32 v75, v75, s6, -v221
	v_fma_f32 v91, v91, s6, -v221
	v_add_f32_e32 v248, v74, v90
	v_exp_f32_e32 v75, v75
	v_exp_f32_e32 v91, v91
	v_add_f32_e32 v249, v248, v249
	v_fma_f32 v76, v76, s6, -v221
	v_fma_f32 v92, v92, s6, -v221
	v_add_f32_e32 v248, v75, v91
	v_exp_f32_e32 v76, v76
	v_exp_f32_e32 v92, v92
	v_add_f32_e32 v249, v248, v249
	v_fma_f32 v77, v77, s6, -v221
	v_fma_f32 v93, v93, s6, -v221
	v_add_f32_e32 v248, v76, v92
	v_exp_f32_e32 v77, v77
	v_exp_f32_e32 v93, v93
	v_add_f32_e32 v249, v248, v249
	v_fma_f32 v78, v78, s6, -v221
	v_fma_f32 v94, v94, s6, -v221
	v_add_f32_e32 v248, v77, v93
	v_exp_f32_e32 v78, v78
	v_exp_f32_e32 v94, v94
	v_add_f32_e32 v249, v248, v249
	v_fma_f32 v79, v79, s6, -v221
	v_fma_f32 v95, v95, s6, -v221
	v_add_f32_e32 v248, v78, v94
	v_exp_f32_e32 v79, v79
	v_exp_f32_e32 v95, v95
	v_add_f32_e32 v249, v248, v249
	s_nop 0
	v_add_f32_e32 v248, v79, v95
	v_add_f32_e32 v249, v248, v249
	v_fmac_f32_e32 v249, v209, v170
	v_cvt_pk_bf16_f32 v198, v64, v65
	v_cvt_pk_bf16_f32 v199, v66, v67
	v_cvt_pk_bf16_f32 v200, v68, v69
	v_cvt_pk_bf16_f32 v201, v70, v71
	v_cvt_pk_bf16_f32 v202, v72, v73
	v_cvt_pk_bf16_f32 v203, v74, v75
	v_cvt_pk_bf16_f32 v204, v76, v77
	v_cvt_pk_bf16_f32 v205, v78, v79
	v_cvt_pk_bf16_f32 v228, v80, v81
	v_cvt_pk_bf16_f32 v229, v82, v83
	v_cvt_pk_bf16_f32 v230, v84, v85
	v_cvt_pk_bf16_f32 v231, v86, v87
	v_cvt_pk_bf16_f32 v232, v88, v89
	v_cvt_pk_bf16_f32 v233, v90, v91
	v_cvt_pk_bf16_f32 v234, v92, v93
	v_cvt_pk_bf16_f32 v235, v94, v95
	v_mov_b32_e32 v209, v249
	v_mov_b32_e32 v247, v221
	s_and_b64 vcc, exec, s[38:39]
	s_cbranch_vccz .Lp_nr_b1f
	v_pk_mul_f32 v[62:63], v[62:63], v[170:171] op_sel_hi:[1,0]
	v_pk_mul_f32 v[60:61], v[60:61], v[170:171] op_sel_hi:[1,0]
	v_pk_mul_f32 v[58:59], v[58:59], v[170:171] op_sel_hi:[1,0]
	v_pk_mul_f32 v[56:57], v[56:57], v[170:171] op_sel_hi:[1,0]
	v_pk_mul_f32 v[54:55], v[54:55], v[170:171] op_sel_hi:[1,0]
	v_pk_mul_f32 v[52:53], v[52:53], v[170:171] op_sel_hi:[1,0]
	v_pk_mul_f32 v[50:51], v[50:51], v[170:171] op_sel_hi:[1,0]
	v_pk_mul_f32 v[48:49], v[48:49], v[170:171] op_sel_hi:[1,0]
	v_pk_mul_f32 v[46:47], v[46:47], v[170:171] op_sel_hi:[1,0]
	v_pk_mul_f32 v[44:45], v[44:45], v[170:171] op_sel_hi:[1,0]
	v_pk_mul_f32 v[42:43], v[42:43], v[170:171] op_sel_hi:[1,0]
	v_pk_mul_f32 v[40:41], v[40:41], v[170:171] op_sel_hi:[1,0]
	v_pk_mul_f32 v[38:39], v[38:39], v[170:171] op_sel_hi:[1,0]
	v_pk_mul_f32 v[36:37], v[36:37], v[170:171] op_sel_hi:[1,0]
	v_pk_mul_f32 v[34:35], v[34:35], v[170:171] op_sel_hi:[1,0]
	v_pk_mul_f32 v[32:33], v[32:33], v[170:171] op_sel_hi:[1,0]
	v_pk_mul_f32 v[30:31], v[30:31], v[170:171] op_sel_hi:[1,0]
	v_pk_mul_f32 v[28:29], v[28:29], v[170:171] op_sel_hi:[1,0]
	v_pk_mul_f32 v[26:27], v[26:27], v[170:171] op_sel_hi:[1,0]
	v_pk_mul_f32 v[24:25], v[24:25], v[170:171] op_sel_hi:[1,0]
	v_pk_mul_f32 v[22:23], v[22:23], v[170:171] op_sel_hi:[1,0]
	v_pk_mul_f32 v[20:21], v[20:21], v[170:171] op_sel_hi:[1,0]
	v_pk_mul_f32 v[18:19], v[18:19], v[170:171] op_sel_hi:[1,0]
	v_pk_mul_f32 v[16:17], v[16:17], v[170:171] op_sel_hi:[1,0]
	v_pk_mul_f32 v[14:15], v[14:15], v[170:171] op_sel_hi:[1,0]
	v_pk_mul_f32 v[12:13], v[12:13], v[170:171] op_sel_hi:[1,0]
	v_pk_mul_f32 v[10:11], v[10:11], v[170:171] op_sel_hi:[1,0]
	v_pk_mul_f32 v[8:9], v[8:9], v[170:171] op_sel_hi:[1,0]
	v_pk_mul_f32 v[6:7], v[6:7], v[170:171] op_sel_hi:[1,0]
	v_pk_mul_f32 v[4:5], v[4:5], v[170:171] op_sel_hi:[1,0]
	v_pk_mul_f32 v[2:3], v[2:3], v[170:171] op_sel_hi:[1,0]
	v_pk_mul_f32 v[0:1], v[0:1], v[170:171] op_sel_hi:[1,0]

.Lp_nomask_b1m:
	v_max3_f32 v227, v64, v65, v66
	v_max3_f32 v248, v73, v74, v75
	v_max3_f32 v249, v80, v81, v82
	v_max3_f32 v170, v89, v90, v91
	v_max3_f32 v227, v227, v67, v68
	v_max3_f32 v248, v248, v76, v77
	v_max3_f32 v249, v249, v83, v84
	v_max3_f32 v170, v170, v92, v93
	v_max3_f32 v227, v227, v69, v70
	s_waitcnt lgkmcnt(6)
	v_mfma_f32_32x32x16_bf16 v[48:63], v[166:169], v[180:183], v[48:63]
	ds_read_b64_tr_b16 v[166:167], v250 offset:64
	ds_read_b64_tr_b16 v[168:169], v250 offset:2624
	v_max3_f32 v248, v248, v78, v79
	v_max3_f32 v249, v249, v85, v86
	v_max3_f32 v170, v170, v94, v95
	v_max3_f32 v227, v227, v71, v72
	v_max3_f32 v249, v249, v87, v88
	v_max3_f32 v227, v227, v248, v226
	v_max3_f32 v227, v227, v249, v170
	v_mov_b32_e32 v248, v227
	s_nop 1
	s_waitcnt lgkmcnt(6)
	v_mfma_f32_32x32x16_bf16 v[48:63], v[172:175], v[184:187], v[48:63]
	ds_read_b64_tr_b16 v[172:173], v250 offset:5184
	ds_read_b64_tr_b16 v[174:175], v250 offset:7744
	v_permlane32_swap_b32_e32 v227, v248
	v_max_f32_e32 v227, v227, v248
	v_mul_f32_e32 v227, 0x3dd53b94, v227
	v_max_f32_e32 v221, v247, v227
	v_sub_f32_e32 v170, v247, v221
	v_exp_f32_e32 v170, v170
	v_cmp_gt_f32_e32 vcc, v221, v247
	s_mov_b64 s[38:39], vcc
	v_fma_f32 v64, v64, s6, -v221
	s_waitcnt lgkmcnt(6)
	v_mfma_f32_32x32x16_bf16 v[48:63], v[176:179], v[190:193], v[48:63]
	ds_read_b64_tr_b16 v[176:177], v250 offset:10304
	ds_read_b64_tr_b16 v[178:179], v250 offset:12864
	v_fma_f32 v80, v80, s6, -v221
	v_exp_f32_e32 v64, v64
	v_exp_f32_e32 v80, v80
	v_fma_f32 v65, v65, s6, -v221
	v_fma_f32 v81, v81, s6, -v221
	v_add_f32_e32 v248, v64, v80
	v_exp_f32_e32 v65, v65
	v_exp_f32_e32 v81, v81
	v_mov_b32_e32 v249, v248
	s_waitcnt lgkmcnt(6)
	v_mfma_f32_32x32x16_bf16 v[48:63], v[222:225], v[194:197], v[48:63]
	ds_read_b64_tr_b16 v[222:223], v250 offset:15424
	ds_read_b64_tr_b16 v[224:225], v250 offset:17984
	v_fma_f32 v66, v66, s6, -v221
	v_fma_f32 v82, v82, s6, -v221
	v_add_f32_e32 v248, v65, v81
	v_exp_f32_e32 v66, v66
	v_exp_f32_e32 v82, v82
	v_add_f32_e32 v249, v248, v249
	v_fma_f32 v67, v67, s6, -v221
	v_fma_f32 v83, v83, s6, -v221
	v_add_f32_e32 v248, v66, v82
	s_waitcnt lgkmcnt(6)
	v_mfma_f32_32x32x16_bf16 v[32:47], v[166:169], v[180:183], v[32:47]
	ds_read_b64_tr_b16 v[166:167], v250 offset:128
	ds_read_b64_tr_b16 v[168:169], v250 offset:2688
	v_exp_f32_e32 v67, v67
	v_exp_f32_e32 v83, v83
	v_add_f32_e32 v249, v248, v249
	v_fma_f32 v68, v68, s6, -v221
	v_fma_f32 v84, v84, s6, -v221
	v_add_f32_e32 v248, v67, v83
	v_exp_f32_e32 v68, v68
	v_exp_f32_e32 v84, v84
	v_add_f32_e32 v249, v248, v249
	s_waitcnt lgkmcnt(6)
	v_mfma_f32_32x32x16_bf16 v[32:47], v[172:175], v[184:187], v[32:47]
	ds_read_b64_tr_b16 v[172:173], v250 offset:5248
	ds_read_b64_tr_b16 v[174:175], v250 offset:7808
	v_fma_f32 v69, v69, s6, -v221
	v_fma_f32 v85, v85, s6, -v221
	v_add_f32_e32 v248, v68, v84
	v_exp_f32_e32 v69, v69
	v_exp_f32_e32 v85, v85
	v_add_f32_e32 v249, v248, v249
	v_fma_f32 v70, v70, s6, -v221
	v_fma_f32 v86, v86, s6, -v221
	v_add_f32_e32 v248, v69, v85
	s_waitcnt lgkmcnt(6)
	v_mfma_f32_32x32x16_bf16 v[32:47], v[176:179], v[190:193], v[32:47]
	ds_read_b64_tr_b16 v[176:177], v250 offset:10368
	ds_read_b64_tr_b16 v[178:179], v250 offset:12928
	v_exp_f32_e32 v70, v70
	v_exp_f32_e32 v86, v86
	v_add_f32_e32 v249, v248, v249
	v_fma_f32 v71, v71, s6, -v221
	v_fma_f32 v87, v87, s6, -v221
	v_add_f32_e32 v248, v70, v86
	v_exp_f32_e32 v71, v71
	v_exp_f32_e32 v87, v87
	v_add_f32_e32 v249, v248, v249
	s_waitcnt lgkmcnt(6)
	v_mfma_f32_32x32x16_bf16 v[32:47], v[222:225], v[194:197], v[32:47]
	ds_read_b64_tr_b16 v[222:223], v250 offset:15488
	ds_read_b64_tr_b16 v[224:225], v250 offset:18048
	v_fma_f32 v72, v72, s6, -v221
	v_fma_f32 v88, v88, s6, -v221
	v_add_f32_e32 v248, v71, v87
	v_exp_f32_e32 v72, v72
	v_exp_f32_e32 v88, v88
	v_add_f32_e32 v249, v248, v249
	v_fma_f32 v73, v73, s6, -v221
	v_fma_f32 v89, v89, s6, -v221
	v_add_f32_e32 v248, v72, v88
	s_waitcnt lgkmcnt(6)
	v_mfma_f32_32x32x16_bf16 v[16:31], v[166:169], v[180:183], v[16:31]
	ds_read_b64_tr_b16 v[166:167], v250 offset:192
	ds_read_b64_tr_b16 v[168:169], v250 offset:2752
	v_exp_f32_e32 v73, v73
	v_exp_f32_e32 v89, v89
	v_add_f32_e32 v249, v248, v249
	v_fma_f32 v74, v74, s6, -v221
	v_fma_f32 v90, v90, s6, -v221
	v_add_f32_e32 v248, v73, v89
	v_exp_f32_e32 v74, v74
	v_exp_f32_e32 v90, v90
	v_add_f32_e32 v249, v248, v249
	s_waitcnt lgkmcnt(6)
	v_mfma_f32_32x32x16_bf16 v[16:31], v[172:175], v[184:187], v[16:31]
	ds_read_b64_tr_b16 v[172:173], v250 offset:5312
	ds_read_b64_tr_b16 v[174:175], v250 offset:7872
	v_fma_f32 v75, v75, s6, -v221
	v_fma_f32 v91, v91, s6, -v221
	v_add_f32_e32 v248, v74, v90
	v_exp_f32_e32 v75, v75
	v_exp_f32_e32 v91, v91
	v_add_f32_e32 v249, v248, v249
	v_fma_f32 v76, v76, s6, -v221
	v_fma_f32 v92, v92, s6, -v221
	v_add_f32_e32 v248, v75, v91
	s_waitcnt lgkmcnt(6)
	v_mfma_f32_32x32x16_bf16 v[16:31], v[176:179], v[190:193], v[16:31]
	ds_read_b64_tr_b16 v[176:177], v250 offset:10432
	ds_read_b64_tr_b16 v[178:179], v250 offset:12992
	v_exp_f32_e32 v76, v76
	v_exp_f32_e32 v92, v92
	v_add_f32_e32 v249, v248, v249
	v_fma_f32 v77, v77, s6, -v221
	v_fma_f32 v93, v93, s6, -v221
	v_add_f32_e32 v248, v76, v92
	v_exp_f32_e32 v77, v77
	v_exp_f32_e32 v93, v93
	v_add_f32_e32 v249, v248, v249
	s_waitcnt lgkmcnt(6)
	v_mfma_f32_32x32x16_bf16 v[16:31], v[222:225], v[194:197], v[16:31]
	ds_read_b64_tr_b16 v[222:223], v250 offset:15552
	ds_read_b64_tr_b16 v[224:225], v250 offset:18112
	v_fma_f32 v78, v78, s6, -v221
	v_fma_f32 v94, v94, s6, -v221
	v_add_f32_e32 v248, v77, v93
	v_exp_f32_e32 v78, v78
	v_exp_f32_e32 v94, v94
	v_add_f32_e32 v249, v248, v249
	v_fma_f32 v79, v79, s6, -v221
	v_fma_f32 v95, v95, s6, -v221
	v_add_f32_e32 v248, v78, v94
	s_waitcnt lgkmcnt(6)
	v_mfma_f32_32x32x16_bf16 v[0:15], v[166:169], v[180:183], v[0:15]
	v_exp_f32_e32 v79, v79
	v_exp_f32_e32 v95, v95
	v_add_f32_e32 v249, v248, v249
	s_nop 0
	v_add_f32_e32 v248, v79, v95
	v_add_f32_e32 v249, v248, v249
	v_fmac_f32_e32 v249, v209, v170
	v_cvt_pk_bf16_f32 v198, v64, v65
	v_cvt_pk_bf16_f32 v199, v66, v67
	s_waitcnt lgkmcnt(4)
	v_mfma_f32_32x32x16_bf16 v[0:15], v[172:175], v[184:187], v[0:15]
	v_cvt_pk_bf16_f32 v200, v68, v69
	v_cvt_pk_bf16_f32 v201, v70, v71
	v_cvt_pk_bf16_f32 v202, v72, v73
	v_cvt_pk_bf16_f32 v203, v74, v75
	v_cvt_pk_bf16_f32 v204, v76, v77
	v_cvt_pk_bf16_f32 v205, v78, v79
	v_cvt_pk_bf16_f32 v228, v80, v81
	v_cvt_pk_bf16_f32 v229, v82, v83
	v_cvt_pk_bf16_f32 v230, v84, v85
	s_waitcnt lgkmcnt(2)
	v_mfma_f32_32x32x16_bf16 v[0:15], v[176:179], v[190:193], v[0:15]
	v_cvt_pk_bf16_f32 v231, v86, v87
	v_cvt_pk_bf16_f32 v232, v88, v89
	v_cvt_pk_bf16_f32 v233, v90, v91
	v_cvt_pk_bf16_f32 v234, v92, v93
	v_cvt_pk_bf16_f32 v235, v94, v95
	v_mov_b32_e32 v209, v249
	v_mov_b32_e32 v247, v221
	s_waitcnt lgkmcnt(0)
	v_mfma_f32_32x32x16_bf16 v[0:15], v[222:225], v[194:197], v[0:15]
	s_and_b64 vcc, exec, s[38:39]
	s_cbranch_vccz .Lp_nr_b1m
	v_pk_mul_f32 v[62:63], v[62:63], v[170:171] op_sel_hi:[1,0]
	v_pk_mul_f32 v[60:61], v[60:61], v[170:171] op_sel_hi:[1,0]
	v_pk_mul_f32 v[58:59], v[58:59], v[170:171] op_sel_hi:[1,0]
	v_pk_mul_f32 v[56:57], v[56:57], v[170:171] op_sel_hi:[1,0]
	v_pk_mul_f32 v[54:55], v[54:55], v[170:171] op_sel_hi:[1,0]
	v_pk_mul_f32 v[52:53], v[52:53], v[170:171] op_sel_hi:[1,0]
	v_pk_mul_f32 v[50:51], v[50:51], v[170:171] op_sel_hi:[1,0]
	v_pk_mul_f32 v[48:49], v[48:49], v[170:171] op_sel_hi:[1,0]
	v_pk_mul_f32 v[46:47], v[46:47], v[170:171] op_sel_hi:[1,0]
	v_pk_mul_f32 v[44:45], v[44:45], v[170:171] op_sel_hi:[1,0]
	v_pk_mul_f32 v[42:43], v[42:43], v[170:171] op_sel_hi:[1,0]
	v_pk_mul_f32 v[40:41], v[40:41], v[170:171] op_sel_hi:[1,0]
	v_pk_mul_f32 v[38:39], v[38:39], v[170:171] op_sel_hi:[1,0]
	v_pk_mul_f32 v[36:37], v[36:37], v[170:171] op_sel_hi:[1,0]
	v_pk_mul_f32 v[34:35], v[34:35], v[170:171] op_sel_hi:[1,0]
	v_pk_mul_f32 v[32:33], v[32:33], v[170:171] op_sel_hi:[1,0]
	v_pk_mul_f32 v[30:31], v[30:31], v[170:171] op_sel_hi:[1,0]
	v_pk_mul_f32 v[28:29], v[28:29], v[170:171] op_sel_hi:[1,0]
	v_pk_mul_f32 v[26:27], v[26:27], v[170:171] op_sel_hi:[1,0]
	v_pk_mul_f32 v[24:25], v[24:25], v[170:171] op_sel_hi:[1,0]
	v_pk_mul_f32 v[22:23], v[22:23], v[170:171] op_sel_hi:[1,0]
	v_pk_mul_f32 v[20:21], v[20:21], v[170:171] op_sel_hi:[1,0]
	v_pk_mul_f32 v[18:19], v[18:19], v[170:171] op_sel_hi:[1,0]
	v_pk_mul_f32 v[16:17], v[16:17], v[170:171] op_sel_hi:[1,0]
	v_pk_mul_f32 v[14:15], v[14:15], v[170:171] op_sel_hi:[1,0]
	v_pk_mul_f32 v[12:13], v[12:13], v[170:171] op_sel_hi:[1,0]
	v_pk_mul_f32 v[10:11], v[10:11], v[170:171] op_sel_hi:[1,0]
	v_pk_mul_f32 v[8:9], v[8:9], v[170:171] op_sel_hi:[1,0]
	v_pk_mul_f32 v[6:7], v[6:7], v[170:171] op_sel_hi:[1,0]
	v_pk_mul_f32 v[4:5], v[4:5], v[170:171] op_sel_hi:[1,0]
	v_pk_mul_f32 v[2:3], v[2:3], v[170:171] op_sel_hi:[1,0]
	v_pk_mul_f32 v[0:1], v[0:1], v[170:171] op_sel_hi:[1,0]

.Lp_novis_b1:
	s_cmp_eq_u32 s46, 0
	s_cbranch_scc1 .Lp_end_b1
	s_sub_i32 s0, s46, 64
	s_cmp_le_i32 s0, s44
	s_cbranch_scc0 .Lp_end_b1
	s_add_i32 s5, s13, -1
	s_mul_i32 s38, s5, 43
	s_lshr_b32 s38, s38, 7
	s_mul_i32 s38, s38, 3
	s_sub_i32 s5, s5, s38
	s_mul_i32 s5, s5, 20480
	s_add_i32 s5, s5, 51200
	v_add_u32_e32 v250, s5, v217
	ds_read_b64_tr_b16 v[166:167], v250 offset:0
	ds_read_b64_tr_b16 v[168:169], v250 offset:2560
	ds_read_b64_tr_b16 v[172:173], v250 offset:5120
	ds_read_b64_tr_b16 v[174:175], v250 offset:7680
	ds_read_b64_tr_b16 v[176:177], v250 offset:10240
	ds_read_b64_tr_b16 v[178:179], v250 offset:12800
	ds_read_b64_tr_b16 v[222:223], v250 offset:15360
	ds_read_b64_tr_b16 v[224:225], v250 offset:17920
	s_nop 1
	s_waitcnt lgkmcnt(6)
	v_mfma_f32_32x32x16_bf16 v[48:63], v[166:169], v[180:183], v[48:63]
	ds_read_b64_tr_b16 v[166:167], v250 offset:64
	ds_read_b64_tr_b16 v[168:169], v250 offset:2624
	s_waitcnt lgkmcnt(6)
	v_mfma_f32_32x32x16_bf16 v[48:63], v[172:175], v[184:187], v[48:63]
	ds_read_b64_tr_b16 v[172:173], v250 offset:5184
	ds_read_b64_tr_b16 v[174:175], v250 offset:7744
	s_waitcnt lgkmcnt(6)
	v_mfma_f32_32x32x16_bf16 v[48:63], v[176:179], v[190:193], v[48:63]
	ds_read_b64_tr_b16 v[176:177], v250 offset:10304
	ds_read_b64_tr_b16 v[178:179], v250 offset:12864
	s_waitcnt lgkmcnt(6)
	v_mfma_f32_32x32x16_bf16 v[48:63], v[222:225], v[194:197], v[48:63]
	ds_read_b64_tr_b16 v[222:223], v250 offset:15424
	ds_read_b64_tr_b16 v[224:225], v250 offset:17984
	s_waitcnt lgkmcnt(6)
	v_mfma_f32_32x32x16_bf16 v[32:47], v[166:169], v[180:183], v[32:47]
	ds_read_b64_tr_b16 v[166:167], v250 offset:128
	ds_read_b64_tr_b16 v[168:169], v250 offset:2688
	s_waitcnt lgkmcnt(6)
	v_mfma_f32_32x32x16_bf16 v[32:47], v[172:175], v[184:187], v[32:47]
	ds_read_b64_tr_b16 v[172:173], v250 offset:5248
	ds_read_b64_tr_b16 v[174:175], v250 offset:7808
	s_waitcnt lgkmcnt(6)
	v_mfma_f32_32x32x16_bf16 v[32:47], v[176:179], v[190:193], v[32:47]
	ds_read_b64_tr_b16 v[176:177], v250 offset:10368
	ds_read_b64_tr_b16 v[178:179], v250 offset:12928
	s_waitcnt lgkmcnt(6)
	v_mfma_f32_32x32x16_bf16 v[32:47], v[222:225], v[194:197], v[32:47]
	ds_read_b64_tr_b16 v[222:223], v250 offset:15488
	ds_read_b64_tr_b16 v[224:225], v250 offset:18048
	s_waitcnt lgkmcnt(6)
	v_mfma_f32_32x32x16_bf16 v[16:31], v[166:169], v[180:183], v[16:31]
	ds_read_b64_tr_b16 v[166:167], v250 offset:192
	ds_read_b64_tr_b16 v[168:169], v250 offset:2752
	s_waitcnt lgkmcnt(6)
	v_mfma_f32_32x32x16_bf16 v[16:31], v[172:175], v[184:187], v[16:31]
	ds_read_b64_tr_b16 v[172:173], v250 offset:5312
	ds_read_b64_tr_b16 v[174:175], v250 offset:7872
	s_waitcnt lgkmcnt(6)
	v_mfma_f32_32x32x16_bf16 v[16:31], v[176:179], v[190:193], v[16:31]
	ds_read_b64_tr_b16 v[176:177], v250 offset:10432
	ds_read_b64_tr_b16 v[178:179], v250 offset:12992
	s_waitcnt lgkmcnt(6)
	v_mfma_f32_32x32x16_bf16 v[16:31], v[222:225], v[194:197], v[16:31]
	ds_read_b64_tr_b16 v[222:223], v250 offset:15552
	ds_read_b64_tr_b16 v[224:225], v250 offset:18112
	s_waitcnt lgkmcnt(6)
	v_mfma_f32_32x32x16_bf16 v[0:15], v[166:169], v[180:183], v[0:15]
	s_waitcnt lgkmcnt(4)
	v_mfma_f32_32x32x16_bf16 v[0:15], v[172:175], v[184:187], v[0:15]
	s_waitcnt lgkmcnt(2)
	v_mfma_f32_32x32x16_bf16 v[0:15], v[176:179], v[190:193], v[0:15]
	s_waitcnt lgkmcnt(0)
	v_mfma_f32_32x32x16_bf16 v[0:15], v[222:225], v[194:197], v[0:15]

.Lp_tail0:
	s_cmp_le_i32 s46, s44
	s_cbranch_scc0 .LBB0_32
	s_mov_b32 s5, s13
	s_mul_i32 s38, s5, 43
	s_lshr_b32 s38, s38, 7
	s_mul_i32 s38, s38, 3
	s_sub_i32 s5, s5, s38
	s_mul_i32 s5, s5, 20480
	s_add_i32 s5, s5, 51200
	v_add_u32_e32 v250, s5, v217
	ds_read_b64_tr_b16 v[166:167], v250 offset:0
	ds_read_b64_tr_b16 v[168:169], v250 offset:2560
	ds_read_b64_tr_b16 v[172:173], v250 offset:5120
	ds_read_b64_tr_b16 v[174:175], v250 offset:7680
	ds_read_b64_tr_b16 v[176:177], v250 offset:10240
	ds_read_b64_tr_b16 v[178:179], v250 offset:12800
	ds_read_b64_tr_b16 v[222:223], v250 offset:15360
	ds_read_b64_tr_b16 v[224:225], v250 offset:17920
	s_nop 1
	s_waitcnt lgkmcnt(6)
	v_mfma_f32_32x32x16_bf16 v[48:63], v[166:169], v[180:183], v[48:63]
	ds_read_b64_tr_b16 v[166:167], v250 offset:64
	ds_read_b64_tr_b16 v[168:169], v250 offset:2624
	s_waitcnt lgkmcnt(6)
	v_mfma_f32_32x32x16_bf16 v[48:63], v[172:175], v[184:187], v[48:63]
	ds_read_b64_tr_b16 v[172:173], v250 offset:5184
	ds_read_b64_tr_b16 v[174:175], v250 offset:7744
	s_waitcnt lgkmcnt(6)
	v_mfma_f32_32x32x16_bf16 v[48:63], v[176:179], v[190:193], v[48:63]
	ds_read_b64_tr_b16 v[176:177], v250 offset:10304
	ds_read_b64_tr_b16 v[178:179], v250 offset:12864
	s_waitcnt lgkmcnt(6)
	v_mfma_f32_32x32x16_bf16 v[48:63], v[222:225], v[194:197], v[48:63]
	ds_read_b64_tr_b16 v[222:223], v250 offset:15424
	ds_read_b64_tr_b16 v[224:225], v250 offset:17984
	s_waitcnt lgkmcnt(6)
	v_mfma_f32_32x32x16_bf16 v[32:47], v[166:169], v[180:183], v[32:47]
	ds_read_b64_tr_b16 v[166:167], v250 offset:128
	ds_read_b64_tr_b16 v[168:169], v250 offset:2688
	s_waitcnt lgkmcnt(6)
	v_mfma_f32_32x32x16_bf16 v[32:47], v[172:175], v[184:187], v[32:47]
	ds_read_b64_tr_b16 v[172:173], v250 offset:5248
	ds_read_b64_tr_b16 v[174:175], v250 offset:7808
	s_waitcnt lgkmcnt(6)
	v_mfma_f32_32x32x16_bf16 v[32:47], v[176:179], v[190:193], v[32:47]
	ds_read_b64_tr_b16 v[176:177], v250 offset:10368
	ds_read_b64_tr_b16 v[178:179], v250 offset:12928
	s_waitcnt lgkmcnt(6)
	v_mfma_f32_32x32x16_bf16 v[32:47], v[222:225], v[194:197], v[32:47]
	ds_read_b64_tr_b16 v[222:223], v250 offset:15488
	ds_read_b64_tr_b16 v[224:225], v250 offset:18048
	s_waitcnt lgkmcnt(6)
	v_mfma_f32_32x32x16_bf16 v[16:31], v[166:169], v[180:183], v[16:31]
	ds_read_b64_tr_b16 v[166:167], v250 offset:192
	ds_read_b64_tr_b16 v[168:169], v250 offset:2752
	s_waitcnt lgkmcnt(6)
	v_mfma_f32_32x32x16_bf16 v[16:31], v[172:175], v[184:187], v[16:31]
	ds_read_b64_tr_b16 v[172:173], v250 offset:5312
	ds_read_b64_tr_b16 v[174:175], v250 offset:7872
	s_waitcnt lgkmcnt(6)
	v_mfma_f32_32x32x16_bf16 v[16:31], v[176:179], v[190:193], v[16:31]
	ds_read_b64_tr_b16 v[176:177], v250 offset:10432
	ds_read_b64_tr_b16 v[178:179], v250 offset:12992
	s_waitcnt lgkmcnt(6)
	v_mfma_f32_32x32x16_bf16 v[16:31], v[222:225], v[194:197], v[16:31]
	ds_read_b64_tr_b16 v[222:223], v250 offset:15552
	ds_read_b64_tr_b16 v[224:225], v250 offset:18112
	s_waitcnt lgkmcnt(6)
	v_mfma_f32_32x32x16_bf16 v[0:15], v[166:169], v[180:183], v[0:15]
	s_waitcnt lgkmcnt(4)
	v_mfma_f32_32x32x16_bf16 v[0:15], v[172:175], v[184:187], v[0:15]
	s_waitcnt lgkmcnt(2)
	v_mfma_f32_32x32x16_bf16 v[0:15], v[176:179], v[190:193], v[0:15]
	s_waitcnt lgkmcnt(0)
	v_mfma_f32_32x32x16_bf16 v[0:15], v[222:225], v[194:197], v[0:15]
	s_branch .LBB0_32
.Lp_tail1:
	s_cmp_le_i32 s46, s44
	s_cbranch_scc0 .LBB0_32
	s_mov_b32 s5, s13
	s_mul_i32 s38, s5, 43
	s_lshr_b32 s38, s38, 7
	s_mul_i32 s38, s38, 3
	s_sub_i32 s5, s5, s38
	s_mul_i32 s5, s5, 20480
	s_add_i32 s5, s5, 51200
	v_add_u32_e32 v250, s5, v217
	ds_read_b64_tr_b16 v[166:167], v250 offset:0
	ds_read_b64_tr_b16 v[168:169], v250 offset:2560
	ds_read_b64_tr_b16 v[172:173], v250 offset:5120
	ds_read_b64_tr_b16 v[174:175], v250 offset:7680
	ds_read_b64_tr_b16 v[176:177], v250 offset:10240
	ds_read_b64_tr_b16 v[178:179], v250 offset:12800
	ds_read_b64_tr_b16 v[222:223], v250 offset:15360
	ds_read_b64_tr_b16 v[224:225], v250 offset:17920
	s_nop 1
	s_waitcnt lgkmcnt(6)
	v_mfma_f32_32x32x16_bf16 v[48:63], v[166:169], v[198:201], v[48:63]
	ds_read_b64_tr_b16 v[166:167], v250 offset:64
	ds_read_b64_tr_b16 v[168:169], v250 offset:2624
	s_waitcnt lgkmcnt(6)
	v_mfma_f32_32x32x16_bf16 v[48:63], v[172:175], v[202:205], v[48:63]
	ds_read_b64_tr_b16 v[172:173], v250 offset:5184
	ds_read_b64_tr_b16 v[174:175], v250 offset:7744
	s_waitcnt lgkmcnt(6)
	v_mfma_f32_32x32x16_bf16 v[48:63], v[176:179], v[228:231], v[48:63]
	ds_read_b64_tr_b16 v[176:177], v250 offset:10304
	ds_read_b64_tr_b16 v[178:179], v250 offset:12864
	s_waitcnt lgkmcnt(6)
	v_mfma_f32_32x32x16_bf16 v[48:63], v[222:225], v[232:235], v[48:63]
	ds_read_b64_tr_b16 v[222:223], v250 offset:15424
	ds_read_b64_tr_b16 v[224:225], v250 offset:17984
	s_waitcnt lgkmcnt(6)
	v_mfma_f32_32x32x16_bf16 v[32:47], v[166:169], v[198:201], v[32:47]
	ds_read_b64_tr_b16 v[166:167], v250 offset:128
	ds_read_b64_tr_b16 v[168:169], v250 offset:2688
	s_waitcnt lgkmcnt(6)
	v_mfma_f32_32x32x16_bf16 v[32:47], v[172:175], v[202:205], v[32:47]
	ds_read_b64_tr_b16 v[172:173], v250 offset:5248
	ds_read_b64_tr_b16 v[174:175], v250 offset:7808
	s_waitcnt lgkmcnt(6)
	v_mfma_f32_32x32x16_bf16 v[32:47], v[176:179], v[228:231], v[32:47]
	ds_read_b64_tr_b16 v[176:177], v250 offset:10368
	ds_read_b64_tr_b16 v[178:179], v250 offset:12928
	s_waitcnt lgkmcnt(6)
	v_mfma_f32_32x32x16_bf16 v[32:47], v[222:225], v[232:235], v[32:47]
	ds_read_b64_tr_b16 v[222:223], v250 offset:15488
	ds_read_b64_tr_b16 v[224:225], v250 offset:18048
	s_waitcnt lgkmcnt(6)
	v_mfma_f32_32x32x16_bf16 v[16:31], v[166:169], v[198:201], v[16:31]
	ds_read_b64_tr_b16 v[166:167], v250 offset:192
	ds_read_b64_tr_b16 v[168:169], v250 offset:2752
	s_waitcnt lgkmcnt(6)
	v_mfma_f32_32x32x16_bf16 v[16:31], v[172:175], v[202:205], v[16:31]
	ds_read_b64_tr_b16 v[172:173], v250 offset:5312
	ds_read_b64_tr_b16 v[174:175], v250 offset:7872
	s_waitcnt lgkmcnt(6)
	v_mfma_f32_32x32x16_bf16 v[16:31], v[176:179], v[228:231], v[16:31]
	ds_read_b64_tr_b16 v[176:177], v250 offset:10432
	ds_read_b64_tr_b16 v[178:179], v250 offset:12992
	s_waitcnt lgkmcnt(6)
	v_mfma_f32_32x32x16_bf16 v[16:31], v[222:225], v[232:235], v[16:31]
	ds_read_b64_tr_b16 v[222:223], v250 offset:15552
	ds_read_b64_tr_b16 v[224:225], v250 offset:18112
	s_waitcnt lgkmcnt(6)
	v_mfma_f32_32x32x16_bf16 v[0:15], v[166:169], v[198:201], v[0:15]
	s_waitcnt lgkmcnt(4)
	v_mfma_f32_32x32x16_bf16 v[0:15], v[172:175], v[202:205], v[0:15]
	s_waitcnt lgkmcnt(2)
	v_mfma_f32_32x32x16_bf16 v[0:15], v[176:179], v[228:231], v[0:15]
	s_waitcnt lgkmcnt(0)
	v_mfma_f32_32x32x16_bf16 v[0:15], v[222:225], v[232:235], v[0:15]
	s_branch .LBB0_32
